# up-GEMM sequence-edge epilogue: the six dependent parameter loads issued early into dead registers, one exposed round trip instead of six
# speedup vs baseline: 1.0160x; 1.0050x over previous
.LBB0_659:
	s_mul_i32 s3, s19, 0xfc
	s_add_i32 s37, s61, s3
	s_add_i32 s8, s37, 0x1080
	s_ashr_i32 s9, s8, 31
	s_lshr_b32 s9, s9, 20
	s_add_i32 s8, s8, s9
	s_mul_i32 s9, s18, 0x1400
	s_add_i32 s83, s9, 0
	v_cvt_f32_i32_e32 v183, v109
	v_cvt_f32_i32_e32 v182, v108
	v_cvt_f32_i32_e32 v181, v105
	v_cvt_f32_i32_e32 v180, v104
	v_cvt_f32_i32_e32 v179, v101
	v_cvt_f32_i32_e32 v178, v100
	v_cvt_f32_i32_e32 v177, v97
	v_cvt_f32_i32_e32 v176, v96
	v_cvt_f32_i32_e32 v125, v125
	v_cvt_f32_i32_e32 v124, v124
	v_cvt_f32_i32_e32 v121, v121
	v_cvt_f32_i32_e32 v120, v120
	v_cvt_f32_i32_e32 v117, v117
	v_cvt_f32_i32_e32 v116, v116
	v_cvt_f32_i32_e32 v113, v113
	v_cvt_f32_i32_e32 v112, v112
	v_cvt_f32_i32_e32 v109, v77
	v_cvt_f32_i32_e32 v108, v76
	v_cvt_f32_i32_e32 v105, v73
	v_cvt_f32_i32_e32 v104, v72
	v_cvt_f32_i32_e32 v101, v69
	v_cvt_f32_i32_e32 v100, v68
	v_cvt_f32_i32_e32 v97, v65
	v_cvt_f32_i32_e32 v96, v64
	v_cvt_f32_i32_e32 v77, v93
	v_cvt_f32_i32_e32 v76, v92
	v_cvt_f32_i32_e32 v73, v89
	v_cvt_f32_i32_e32 v72, v88
	v_cvt_f32_i32_e32 v69, v85
	v_cvt_f32_i32_e32 v68, v84
	v_cvt_f32_i32_e32 v65, v81
	v_cvt_f32_i32_e32 v64, v80
	s_add_i32 s83, s83, 0x20340
	s_lshl_b32 s9, s60, 2
	s_add_i32 s3, s37, 0x1000
	s_and_b32 s8, s8, 0xfffff000
	s_add_i32 s33, s83, s9
	s_cmp_lt_i32 s8, s3
	s_cbranch_scc1 .LBB0_685
	v_mbcnt_lo_u32_b32 v80, -1, 0
	v_mbcnt_hi_u32_b32 v80, -1, v80
	s_lshl_b32 s3, s95, 7
	v_and_b32_e32 v81, 15, v80
	v_ashrrev_i32_e32 v84, 4, v80
	s_or_b32 s3, s3, s73
	v_lshl_add_u32 v80, v81, 5, s33
	v_add_u32_e32 v85, 0x1000, v80
	v_add_u32_e32 v80, 0x1010, v80
	ds_read2_b64 v[132:135], v85 offset1:1
	ds_read2_b64 v[128:131], v80 offset1:1
	v_lshl_add_u32 v80, v84, 2, s3
	s_lshl_b32 s3, s73, 2
	v_lshlrev_b32_e32 v185, 3, v81
	v_ashrrev_i32_e32 v81, 31, v80
	s_add_i32 s3, s83, s3
	v_lshlrev_b64 v[88:89], 2, v[80:81]
	s_mov_b64 s[8:9], 0x2c00
	v_lshl_add_u32 v202, v84, 4, s3
	v_lshl_add_u64 v[92:93], v[88:89], 0, s[8:9]
	v_add_u32_e32 v196, 0x800, v202
	v_lshl_add_u64 v[152:153], s[28:29], 0, v[92:93]
	ds_read2_b64 v[136:139], v196 offset1:1
	ds_read2_b64 v[144:147], v196 offset0:64 offset1:65
	ds_read2_b64 v[140:143], v196 offset0:128 offset1:129
	ds_read2_b64 v[148:151], v196 offset0:192 offset1:193
	global_load_dwordx2 v[152:153], v[152:153], off
	global_load_dword v227, v92, s[28:29] offset:8
	global_load_dword v220, v92, s[28:29] offset:12
	global_load_dword v237, v92, s[26:27] offset:8
	global_load_dword v241, v92, s[26:27] offset:12
	v_lshl_add_u64 v[92:93], s[26:27], 0, v[92:93]
	global_load_dwordx2 v[92:93], v[92:93], off
	v_lshl_add_u64 v[242:243], s[28:29], 0, v[88:89]
	v_lshl_add_u64 v[246:247], s[26:27], 0, v[88:89]
	global_load_dwordx4 v[242:245], v[242:243], off
	global_load_dwordx4 v[246:249], v[246:247], off
	s_mov_b32 s42, 0x3c010204
	v_add_u32_e32 v85, s37, v185
	v_and_b32_e32 v171, 0xfff, v85
	s_movk_i32 s3, 0xfff
	s_waitcnt lgkmcnt(0)
	v_pk_mul_f32 v[166:167], v[132:133], v[182:183] op_sel_hi:[0,1]
	v_pk_mul_f32 v[168:169], v[132:133], v[180:181] op_sel:[1,0]
	v_pk_fma_f32 v[174:175], v[144:145], v[166:167], v[148:149]
	v_pk_mul_f32 v[162:163], v[134:135], v[178:179] op_sel_hi:[0,1]
	v_mov_b32_e32 v184, v135
	v_pk_mul_f32 v[160:161], v[184:185], v[176:177] op_sel_hi:[0,1]
	v_pk_mul_f32 v[158:159], v[128:129], v[124:125] op_sel_hi:[0,1]
	s_mov_b32 s24, 0x3856241d
	v_pk_mul_f32 v[198:199], v[134:135], v[100:101] op_sel_hi:[0,1]
	v_pk_mul_f32 v[200:201], v[184:185], v[96:97] op_sel_hi:[0,1]
	v_pk_mul_f32 v[204:205], v[128:129], v[76:77] op_sel_hi:[0,1]
	v_pk_mul_f32 v[206:207], v[128:129], v[72:73] op_sel:[1,0]
	v_pk_mul_f32 v[208:209], v[130:131], v[68:69] op_sel_hi:[0,1]
	s_waitcnt vmcnt(0)
	v_max_f32_e32 v81, v152, v152
	v_max_f32_e32 v152, 0xda24260, v81
	v_max_f32_e32 v81, v153, v153
	v_max_f32_e32 v153, 0xda24260, v81
	v_pk_add_f32 v[92:93], v[92:93], 0 neg_lo:[1,1] neg_hi:[1,1]
	v_pk_mul_f32 v[152:153], v[152:153], s[42:43] op_sel_hi:[1,0]
	s_nop 0
	v_div_scale_f32 v81, s[8:9], v152, v152, v92
	v_rcp_f32_e32 v84, v81
	s_nop 0
	v_fma_f32 v154, -v81, v84, 1.0
	v_fmac_f32_e32 v84, v154, v84
	v_div_scale_f32 v154, vcc, v92, v152, v92
	v_mul_f32_e32 v155, v154, v84
	v_fma_f32 v156, -v81, v155, v154
	v_fmac_f32_e32 v155, v156, v84
	v_fma_f32 v81, -v81, v155, v154
	v_div_fmas_f32 v81, v81, v84, v155
	v_div_scale_f32 v84, s[8:9], v153, v153, v93
	v_div_fixup_f32 v81, v81, v152, v92
	v_rcp_f32_e32 v92, v84
	v_cmp_eq_u32_e64 s[8:9], s3, v171
	v_add_u32_e32 v171, 1, v85
	v_and_b32_e32 v171, 0xffe, v171
	v_fma_f32 v152, -v84, v92, 1.0
	v_fmac_f32_e32 v92, v152, v92
	v_div_scale_f32 v152, vcc, v93, v153, v93
	v_mul_f32_e32 v154, v152, v92
	v_fma_f32 v155, -v84, v154, v152
	v_fmac_f32_e32 v154, v155, v92
	v_fma_f32 v84, -v84, v154, v152
	v_cmp_eq_u32_e64 s[10:11], 0, v171
	v_sub_u32_e32 v171, 0xffd, v85
	v_div_fmas_f32 v84, v84, v92, v154
	v_and_b32_e32 v171, 0xffe, v171
	v_div_fixup_f32 v170, v84, v153, v93
	v_mov_b32_e32 v84, v131
	v_cmp_eq_u32_e64 s[12:13], 0, v171
	v_add_u32_e32 v171, 3, v85
	v_pk_mul_f32 v[92:93], v[84:85], v[112:113] op_sel_hi:[0,1]
	v_and_b32_e32 v171, 0xffe, v171
	v_mov_b32_e32 v164, v92
	v_mov_b32_e32 v165, v93
	v_cmp_eq_u32_e64 s[14:15], 0, v171
	v_sub_u32_e32 v171, 0xffb, v85
	v_mov_b32_dpp v164, v164 row_shr:1 row_mask:0xf bank_mask:0xf
	v_mov_b32_dpp v165, v165 row_shr:1 row_mask:0xf bank_mask:0xf
	v_and_b32_e32 v171, 0xffe, v171
	v_cndmask_b32_e64 v173, v169, v170, s[8:9]
	v_cndmask_b32_e64 v172, v168, v81, s[8:9]
	v_pk_fma_f32 v[164:165], v[136:137], v[164:165], v[174:175]
	v_cmp_eq_u32_e64 s[22:23], 0, v171
	v_add_u32_e32 v171, 5, v85
	v_mov_b32_e32 v154, v166
	v_mov_b32_e32 v155, v167
	v_pk_fma_f32 v[164:165], v[140:141], v[172:173], v[164:165]
	v_cndmask_b32_e64 v167, v167, v170, s[10:11]
	v_cndmask_b32_e64 v166, v166, v81, s[10:11]
	v_pk_fma_f32 v[172:173], v[144:145], v[168:169], v[148:149]
	v_pk_fma_f32 v[174:175], v[144:145], v[162:163], v[148:149]
	v_and_b32_e32 v171, 0xffe, v171
	v_pk_fma_f32 v[166:167], v[136:137], v[166:167], v[172:173]
	v_cndmask_b32_e64 v173, v161, v170, s[12:13]
	v_cndmask_b32_e64 v172, v160, v81, s[12:13]
	v_pk_fma_f32 v[168:169], v[136:137], v[168:169], v[174:175]
	v_cmp_eq_u32_e64 s[20:21], 0, v171
	v_sub_u32_e32 v171, 0xff9, v85
	v_pk_mul_f32 v[156:157], v[128:129], v[120:121] op_sel:[1,0]
	v_pk_fma_f32 v[166:167], v[140:141], v[162:163], v[166:167]
	v_pk_fma_f32 v[168:169], v[140:141], v[172:173], v[168:169]
	v_cndmask_b32_e64 v163, v163, v170, s[14:15]
	v_cndmask_b32_e64 v162, v162, v81, s[14:15]
	v_pk_fma_f32 v[172:173], v[144:145], v[160:161], v[148:149]
	v_pk_fma_f32 v[174:175], v[144:145], v[158:159], v[148:149]
	v_and_b32_e32 v171, 0xffe, v171
	v_pk_fma_f32 v[162:163], v[136:137], v[162:163], v[172:173]
	v_cndmask_b32_e64 v173, v157, v170, s[22:23]
	v_cndmask_b32_e64 v172, v156, v81, s[22:23]
	v_pk_fma_f32 v[160:161], v[136:137], v[160:161], v[174:175]
	v_cmp_eq_u32_e64 s[18:19], 0, v171
	v_add_u32_e32 v171, 7, v85
	v_pk_fma_f32 v[162:163], v[140:141], v[158:159], v[162:163]
	v_pk_fma_f32 v[160:161], v[140:141], v[172:173], v[160:161]
	v_cndmask_b32_e64 v159, v159, v170, s[20:21]
	v_cndmask_b32_e64 v158, v158, v81, s[20:21]
	v_pk_fma_f32 v[172:173], v[144:145], v[156:157], v[148:149]
	v_and_b32_e32 v171, 0xffe, v171
	v_pk_mul_f32 v[152:153], v[130:131], v[116:117] op_sel_hi:[0,1]
	v_pk_fma_f32 v[158:159], v[136:137], v[158:159], v[172:173]
	v_cmp_eq_u32_e64 s[16:17], 0, v171
	v_pk_fma_f32 v[158:159], v[140:141], v[152:153], v[158:159]
	v_cndmask_b32_e64 v173, v93, v170, s[18:19]
	v_cndmask_b32_e64 v172, v92, v81, s[18:19]
	v_pk_fma_f32 v[174:175], v[144:145], v[152:153], v[148:149]
	v_cndmask_b32_e64 v153, v153, v170, s[16:17]
	v_cndmask_b32_e64 v152, v152, v81, s[16:17]
	v_pk_fma_f32 v[92:93], v[144:145], v[92:93], v[148:149]
	v_mov_b32_dpp v154, v154 row_shl:1 row_mask:0xf bank_mask:0xf
	v_mov_b32_dpp v155, v155 row_shl:1 row_mask:0xf bank_mask:0xf
	v_pk_fma_f32 v[156:157], v[136:137], v[156:157], v[174:175]
	v_pk_fma_f32 v[92:93], v[136:137], v[152:153], v[92:93]
	v_pk_fma_f32 v[156:157], v[140:141], v[172:173], v[156:157]
	v_pk_fma_f32 v[92:93], v[140:141], v[154:155], v[92:93]
	v_and_b32_e32 v141, 0x7fffffff, v165
	v_and_b32_e32 v140, 0x7fffffff, v164
	v_mov_b64_e32 v[136:137], s[24:25]
	v_pk_fma_f32 v[144:145], v[140:141], s[80:81], v[136:137] op_sel_hi:[1,0,0]
	v_and_b32_e32 v149, 0x7fffffff, v167
	v_pk_fma_f32 v[144:145], v[140:141], v[144:145], s[84:85] op_sel_hi:[1,1,0]
	v_and_b32_e32 v148, 0x7fffffff, v166
	v_pk_fma_f32 v[144:145], v[140:141], v[144:145], s[86:87] op_sel_hi:[1,1,0]
	v_pk_fma_f32 v[186:187], v[148:149], s[80:81], v[136:137] op_sel_hi:[1,0,0]
	v_pk_fma_f32 v[144:145], v[140:141], v[144:145], s[82:83] op_sel_hi:[1,1,0]
	v_pk_fma_f32 v[186:187], v[148:149], v[186:187], s[84:85] op_sel_hi:[1,1,0]
	v_pk_fma_f32 v[144:145], v[140:141], v[144:145], s[94:95] op_sel_hi:[1,1,0]
	v_pk_fma_f32 v[186:187], v[148:149], v[186:187], s[86:87] op_sel_hi:[1,1,0]
	v_pk_fma_f32 v[144:145], v[140:141], v[144:145], s[92:93] op_sel_hi:[1,1,0]
	v_and_b32_e32 v175, 0x7fffffff, v169
	v_pk_mul_f32 v[144:145], v[144:145], v[144:145]
	v_and_b32_e32 v174, 0x7fffffff, v168
	v_pk_fma_f32 v[186:187], v[148:149], v[186:187], s[82:83] op_sel_hi:[1,1,0]
	v_pk_mul_f32 v[144:145], v[144:145], v[144:145]
	v_pk_fma_f32 v[188:189], v[174:175], s[80:81], v[136:137] op_sel_hi:[1,0,0]
	v_pk_fma_f32 v[186:187], v[148:149], v[186:187], s[94:95] op_sel_hi:[1,1,0]
	v_pk_mul_f32 v[144:145], v[144:145], v[144:145]
	v_pk_fma_f32 v[188:189], v[174:175], v[188:189], s[84:85] op_sel_hi:[1,1,0]
	v_pk_fma_f32 v[186:187], v[148:149], v[186:187], s[92:93] op_sel_hi:[1,1,0]
	v_pk_mul_f32 v[144:145], v[144:145], v[144:145]
	v_pk_fma_f32 v[188:189], v[174:175], v[188:189], s[86:87] op_sel_hi:[1,1,0]
	v_pk_mul_f32 v[186:187], v[186:187], v[186:187]
	v_rcp_f32_e32 v144, v144
	v_rcp_f32_e32 v145, v145
	v_and_b32_e32 v173, 0x7fffffff, v163
	v_and_b32_e32 v172, 0x7fffffff, v162
	v_pk_fma_f32 v[188:189], v[174:175], v[188:189], s[82:83] op_sel_hi:[1,1,0]
	v_pk_mul_f32 v[186:187], v[186:187], v[186:187]
	v_pk_fma_f32 v[190:191], v[172:173], s[80:81], v[136:137] op_sel_hi:[1,0,0]
	v_pk_fma_f32 v[188:189], v[174:175], v[188:189], s[94:95] op_sel_hi:[1,1,0]
	v_pk_mul_f32 v[186:187], v[186:187], v[186:187]
	v_pk_fma_f32 v[190:191], v[172:173], v[190:191], s[84:85] op_sel_hi:[1,1,0]
	v_pk_fma_f32 v[188:189], v[174:175], v[188:189], s[92:93] op_sel_hi:[1,1,0]
	v_pk_mul_f32 v[192:193], v[186:187], v[186:187]
	v_max_f32_e32 v165, 0, v165
	v_max_f32_e32 v164, 0, v164
	v_pk_fma_f32 v[190:191], v[172:173], v[190:191], s[86:87] op_sel_hi:[1,1,0]
	v_pk_mul_f32 v[188:189], v[188:189], v[188:189]
	v_pk_fma_f32 v[186:187], v[140:141], v[144:145], v[164:165] neg_lo:[1,0,0] neg_hi:[1,0,0]
	v_rcp_f32_e32 v140, v192
	v_rcp_f32_e32 v141, v193
	v_pk_fma_f32 v[190:191], v[172:173], v[190:191], s[82:83] op_sel_hi:[1,1,0]
	v_pk_mul_f32 v[188:189], v[188:189], v[188:189]
	v_pk_fma_f32 v[190:191], v[172:173], v[190:191], s[94:95] op_sel_hi:[1,1,0]
	v_pk_mul_f32 v[188:189], v[188:189], v[188:189]
	v_pk_fma_f32 v[190:191], v[172:173], v[190:191], s[92:93] op_sel_hi:[1,1,0]
	v_pk_mul_f32 v[188:189], v[188:189], v[188:189]
	v_max_f32_e32 v145, 0, v167
	v_max_f32_e32 v144, 0, v166
	v_pk_mul_f32 v[190:191], v[190:191], v[190:191]
	v_pk_fma_f32 v[148:149], v[148:149], v[140:141], v[144:145] neg_lo:[1,0,0] neg_hi:[1,0,0]
	v_rcp_f32_e32 v140, v188
	v_rcp_f32_e32 v141, v189
	v_pk_mul_f32 v[190:191], v[190:191], v[190:191]
	v_max_f32_e32 v145, 0, v169
	v_pk_mul_f32 v[190:191], v[190:191], v[190:191]
	v_max_f32_e32 v144, 0, v168
	v_pk_mul_f32 v[190:191], v[190:191], v[190:191]
	v_pk_fma_f32 v[144:145], v[174:175], v[140:141], v[144:145] neg_lo:[1,0,0] neg_hi:[1,0,0]
	v_rcp_f32_e32 v140, v190
	v_rcp_f32_e32 v141, v191
	v_max_f32_e32 v163, 0, v163
	v_max_f32_e32 v162, 0, v162
	v_and_b32_e32 v171, 0x7fffffff, v159
	v_pk_fma_f32 v[140:141], v[172:173], v[140:141], v[162:163] neg_lo:[1,0,0] neg_hi:[1,0,0]
	v_and_b32_e32 v163, 0x7fffffff, v161
	v_and_b32_e32 v162, 0x7fffffff, v160
	v_pk_fma_f32 v[164:165], v[162:163], s[80:81], v[136:137] op_sel_hi:[1,0,0]
	v_and_b32_e32 v170, 0x7fffffff, v158
	v_pk_fma_f32 v[164:165], v[162:163], v[164:165], s[84:85] op_sel_hi:[1,1,0]
	v_pk_fma_f32 v[166:167], v[170:171], s[80:81], v[136:137] op_sel_hi:[1,0,0]
	v_pk_fma_f32 v[164:165], v[162:163], v[164:165], s[86:87] op_sel_hi:[1,1,0]
	v_pk_fma_f32 v[166:167], v[170:171], v[166:167], s[84:85] op_sel_hi:[1,1,0]
	v_pk_fma_f32 v[164:165], v[162:163], v[164:165], s[82:83] op_sel_hi:[1,1,0]
	v_pk_fma_f32 v[166:167], v[170:171], v[166:167], s[86:87] op_sel_hi:[1,1,0]
	v_pk_fma_f32 v[164:165], v[162:163], v[164:165], s[94:95] op_sel_hi:[1,1,0]
	v_and_b32_e32 v155, 0x7fffffff, v157
	v_pk_fma_f32 v[164:165], v[162:163], v[164:165], s[92:93] op_sel_hi:[1,1,0]
	v_and_b32_e32 v154, 0x7fffffff, v156
	v_pk_mul_f32 v[164:165], v[164:165], v[164:165]
	v_pk_fma_f32 v[166:167], v[170:171], v[166:167], s[82:83] op_sel_hi:[1,1,0]
	v_pk_mul_f32 v[164:165], v[164:165], v[164:165]
	v_pk_fma_f32 v[168:169], v[154:155], s[80:81], v[136:137] op_sel_hi:[1,0,0]
	v_pk_fma_f32 v[166:167], v[170:171], v[166:167], s[94:95] op_sel_hi:[1,1,0]
	v_pk_mul_f32 v[164:165], v[164:165], v[164:165]
	v_pk_fma_f32 v[168:169], v[154:155], v[168:169], s[84:85] op_sel_hi:[1,1,0]
	v_pk_fma_f32 v[166:167], v[170:171], v[166:167], s[92:93] op_sel_hi:[1,1,0]
	v_pk_mul_f32 v[164:165], v[164:165], v[164:165]
	v_pk_fma_f32 v[168:169], v[154:155], v[168:169], s[86:87] op_sel_hi:[1,1,0]
	v_pk_mul_f32 v[166:167], v[166:167], v[166:167]
	v_rcp_f32_e32 v164, v164
	v_rcp_f32_e32 v165, v165
	v_and_b32_e32 v153, 0x7fffffff, v93
	v_and_b32_e32 v152, 0x7fffffff, v92
	v_pk_fma_f32 v[168:169], v[154:155], v[168:169], s[82:83] op_sel_hi:[1,1,0]
	v_pk_mul_f32 v[166:167], v[166:167], v[166:167]
	v_pk_fma_f32 v[172:173], v[152:153], s[80:81], v[136:137] op_sel_hi:[1,0,0]
	v_pk_fma_f32 v[168:169], v[154:155], v[168:169], s[94:95] op_sel_hi:[1,1,0]
	v_pk_mul_f32 v[166:167], v[166:167], v[166:167]
	v_pk_fma_f32 v[172:173], v[152:153], v[172:173], s[84:85] op_sel_hi:[1,1,0]
	v_pk_fma_f32 v[168:169], v[154:155], v[168:169], s[92:93] op_sel_hi:[1,1,0]
	v_pk_mul_f32 v[166:167], v[166:167], v[166:167]
	v_max_f32_e32 v161, 0, v161
	v_max_f32_e32 v160, 0, v160
	v_pk_fma_f32 v[172:173], v[152:153], v[172:173], s[86:87] op_sel_hi:[1,1,0]
	v_pk_mul_f32 v[168:169], v[168:169], v[168:169]
	v_pk_fma_f32 v[194:195], v[162:163], v[164:165], v[160:161] neg_lo:[1,0,0] neg_hi:[1,0,0]
	v_rcp_f32_e32 v160, v166
	v_rcp_f32_e32 v161, v167
	v_pk_fma_f32 v[172:173], v[152:153], v[172:173], s[82:83] op_sel_hi:[1,1,0]
	v_pk_mul_f32 v[168:169], v[168:169], v[168:169]
	v_pk_fma_f32 v[172:173], v[152:153], v[172:173], s[94:95] op_sel_hi:[1,1,0]
	v_pk_mul_f32 v[168:169], v[168:169], v[168:169]
	v_pk_fma_f32 v[172:173], v[152:153], v[172:173], s[92:93] op_sel_hi:[1,1,0]
	v_pk_mul_f32 v[168:169], v[168:169], v[168:169]
	v_max_f32_e32 v159, 0, v159
	v_max_f32_e32 v158, 0, v158
	v_pk_mul_f32 v[172:173], v[172:173], v[172:173]
	v_pk_fma_f32 v[192:193], v[170:171], v[160:161], v[158:159] neg_lo:[1,0,0] neg_hi:[1,0,0]
	v_rcp_f32_e32 v158, v168
	v_rcp_f32_e32 v159, v169
	v_pk_mul_f32 v[172:173], v[172:173], v[172:173]
	v_max_f32_e32 v157, 0, v157
	v_pk_mul_f32 v[172:173], v[172:173], v[172:173]
	v_max_f32_e32 v156, 0, v156
	v_pk_mul_f32 v[172:173], v[172:173], v[172:173]
	v_pk_fma_f32 v[190:191], v[154:155], v[158:159], v[156:157] neg_lo:[1,0,0] neg_hi:[1,0,0]
	v_rcp_f32_e32 v154, v172
	v_rcp_f32_e32 v155, v173
	v_max_f32_e32 v93, 0, v93
	v_max_f32_e32 v92, 0, v92
	v_pk_mul_f32 v[210:211], v[84:85], v[64:65] op_sel_hi:[0,1]
	v_pk_fma_f32 v[188:189], v[152:153], v[154:155], v[92:93] neg_lo:[1,0,0] neg_hi:[1,0,0]
	v_lshl_add_u64 v[92:93], s[28:29], 0, v[88:89]
	ds_read2_b64 v[156:159], v202 offset0:64 offset1:65
	ds_read2_b64 v[152:155], v202 offset0:128 offset1:129
	ds_read2_b64 v[160:163], v202 offset0:192 offset1:193
	v_mov_b64_e32 v[164:165], v[242:243]
	v_mov_b64_e32 v[166:167], v[244:245]
	v_lshl_add_u64 v[88:89], s[26:27], 0, v[88:89]
	v_mov_b64_e32 v[168:169], v[246:247]
	v_mov_b64_e32 v[170:171], v[248:249]
	v_mov_b32_e32 v212, v210
	v_mov_b32_e32 v213, v211
	s_movk_i32 s3, 0x2000
	v_mov_b32_dpp v212, v212 row_shr:1 row_mask:0xf bank_mask:0xf
	v_mov_b32_dpp v213, v213 row_shr:1 row_mask:0xf bank_mask:0xf
	s_waitcnt vmcnt(1)
	v_max_f32_e32 v81, v164, v164
	v_max_f32_e32 v164, 0xda24260, v81
	v_max_f32_e32 v81, v165, v165
	v_max_f32_e32 v165, 0xda24260, v81
	s_waitcnt vmcnt(0)
	v_pk_add_f32 v[168:169], v[168:169], 0 neg_lo:[1,1] neg_hi:[1,1]
	v_pk_mul_f32 v[164:165], v[164:165], s[42:43] op_sel_hi:[1,0]
	s_nop 0
	v_div_scale_f32 v81, s[24:25], v164, v164, v168
	v_rcp_f32_e32 v172, v81
	s_nop 0
	v_fma_f32 v173, -v81, v172, 1.0
	v_fmac_f32_e32 v172, v173, v172
	v_div_scale_f32 v173, vcc, v168, v164, v168
	v_mul_f32_e32 v174, v173, v172
	v_fma_f32 v175, -v81, v174, v173
	v_fmac_f32_e32 v174, v175, v172
	v_fma_f32 v81, -v81, v174, v173
	v_div_fmas_f32 v81, v81, v172, v174
	v_div_fixup_f32 v81, v81, v164, v168
	v_div_scale_f32 v164, s[24:25], v165, v165, v169
	v_rcp_f32_e32 v168, v164
	s_nop 0
	v_fma_f32 v172, -v164, v168, 1.0
	v_fmac_f32_e32 v168, v172, v168
	v_div_scale_f32 v172, vcc, v169, v165, v169
	v_mul_f32_e32 v173, v172, v168
	v_fma_f32 v174, -v164, v173, v172
	v_fmac_f32_e32 v173, v174, v168
	v_fma_f32 v164, -v164, v173, v172
	v_div_fmas_f32 v164, v164, v168, v173
	ds_read2_b64 v[172:175], v202 offset1:1
	v_div_fixup_f32 v203, v164, v165, v169
	v_pk_mul_f32 v[164:165], v[132:133], v[108:109] op_sel_hi:[0,1]
	v_pk_mul_f32 v[168:169], v[132:133], v[104:105] op_sel:[1,0]
	s_waitcnt lgkmcnt(1)
	v_pk_fma_f32 v[218:219], v[156:157], v[164:165], v[160:161]
	v_cndmask_b32_e64 v217, v169, v203, s[8:9]
	v_cndmask_b32_e64 v216, v168, v81, s[8:9]
	s_waitcnt lgkmcnt(0)
	v_pk_fma_f32 v[212:213], v[172:173], v[212:213], v[218:219]
	v_mov_b32_e32 v214, v164
	v_pk_fma_f32 v[212:213], v[152:153], v[216:217], v[212:213]
	v_mov_b32_e32 v215, v165
	v_pk_mul_f32 v[186:187], v[212:213], v[186:187]
	v_cndmask_b32_e64 v165, v165, v203, s[10:11]
	v_cvt_pk_fp8_f32 v197, v186, v187
	s_nop 0
	v_cndmask_b32_e64 v164, v164, v81, s[10:11]
	v_pk_fma_f32 v[186:187], v[156:157], v[168:169], v[160:161]
	v_mov_b32_dpp v214, v214 row_shl:1 row_mask:0xf bank_mask:0xf
	v_pk_fma_f32 v[164:165], v[172:173], v[164:165], v[186:187]
	v_mov_b32_dpp v215, v215 row_shl:1 row_mask:0xf bank_mask:0xf
	v_pk_fma_f32 v[164:165], v[152:153], v[198:199], v[164:165]
	s_nop 0
	v_pk_mul_f32 v[148:149], v[164:165], v[148:149]
	v_pk_fma_f32 v[164:165], v[156:157], v[198:199], v[160:161]
	v_cvt_pk_fp8_f32 v187, v148, v149
	s_nop 0
	v_cndmask_b32_e64 v149, v201, v203, s[12:13]
	v_cndmask_b32_e64 v148, v200, v81, s[12:13]
	v_pk_fma_f32 v[164:165], v[172:173], v[168:169], v[164:165]
	s_nop 0
	v_pk_fma_f32 v[148:149], v[152:153], v[148:149], v[164:165]
	s_nop 0
	v_pk_mul_f32 v[144:145], v[148:149], v[144:145]
	v_pk_fma_f32 v[148:149], v[156:157], v[200:201], v[160:161]
	v_cvt_pk_fp8_f32 v186, v144, v145
	s_nop 0
	v_cndmask_b32_e64 v145, v199, v203, s[14:15]
	v_cndmask_b32_e64 v144, v198, v81, s[14:15]
	v_pk_fma_f32 v[144:145], v[172:173], v[144:145], v[148:149]
	s_nop 0
	v_pk_fma_f32 v[144:145], v[152:153], v[204:205], v[144:145]
	s_nop 0
	v_pk_mul_f32 v[140:141], v[144:145], v[140:141]
	v_pk_fma_f32 v[144:145], v[156:157], v[204:205], v[160:161]
	v_cvt_pk_fp8_f32 v169, v140, v141
	s_nop 0
	v_cndmask_b32_e64 v141, v207, v203, s[22:23]
	v_cndmask_b32_e64 v140, v206, v81, s[22:23]
	v_pk_fma_f32 v[144:145], v[172:173], v[200:201], v[144:145]
	s_nop 0
	v_pk_fma_f32 v[140:141], v[152:153], v[140:141], v[144:145]
	v_pk_fma_f32 v[144:145], v[156:157], v[206:207], v[160:161]
	v_pk_mul_f32 v[140:141], v[140:141], v[194:195]
	s_nop 0
	v_cvt_pk_fp8_f32 v168, v140, v141
	s_nop 0
	v_cndmask_b32_e64 v141, v205, v203, s[20:21]
	v_cndmask_b32_e64 v140, v204, v81, s[20:21]
	v_pk_fma_f32 v[140:141], v[172:173], v[140:141], v[144:145]
	v_pk_fma_f32 v[144:145], v[156:157], v[208:209], v[160:161]
	v_pk_fma_f32 v[140:141], v[152:153], v[208:209], v[140:141]
	v_pk_fma_f32 v[144:145], v[172:173], v[206:207], v[144:145]
	v_pk_mul_f32 v[140:141], v[140:141], v[192:193]
	s_nop 0
	v_cvt_pk_fp8_f32 v165, v140, v141
	s_nop 0
	v_cndmask_b32_e64 v141, v211, v203, s[18:19]
	v_cndmask_b32_e64 v140, v210, v81, s[18:19]
	v_pk_fma_f32 v[140:141], v[152:153], v[140:141], v[144:145]
	v_pk_fma_f32 v[144:145], v[156:157], v[210:211], v[160:161]
	v_pk_mul_f32 v[140:141], v[140:141], v[190:191]
	v_cvt_f32_i32_e32 v157, v127
	v_cvt_pk_fp8_f32 v164, v140, v141
	s_nop 0
	v_cndmask_b32_e64 v141, v209, v203, s[16:17]
	v_cndmask_b32_e64 v140, v208, v81, s[16:17]
	v_pk_fma_f32 v[140:141], v[172:173], v[140:141], v[144:145]
	v_cvt_f32_i32_e32 v161, v123
	v_pk_fma_f32 v[140:141], v[152:153], v[214:215], v[140:141]
	v_cvt_f32_i32_e32 v160, v122
	v_pk_mul_f32 v[140:141], v[140:141], v[188:189]
	v_cvt_f32_i32_e32 v189, v115
	v_cvt_pk_fp8_f32 v81, v140, v141
	s_nop 0
	v_add_co_u32_e32 v140, vcc, s3, v92
	v_cvt_f32_i32_e32 v188, v114
	s_nop 0
	v_addc_co_u32_e32 v141, vcc, 0, v93, vcc
	v_mov_b32_e32 v140, v227
	v_mov_b32_e32 v141, v220
	v_add_co_u32_e32 v144, vcc, s3, v88
	v_pk_mul_f32 v[188:189], v[84:85], v[188:189] op_sel_hi:[0,1]
	s_nop 0
	v_addc_co_u32_e32 v145, vcc, 0, v89, vcc
	v_mov_b32_e32 v144, v237
	v_mov_b32_e32 v145, v241
	v_mov_b32_e32 v190, v188
	v_mov_b32_e32 v191, v189
	v_cvt_f32_i32_e32 v173, v119
	v_mov_b32_dpp v190, v190 row_shr:1 row_mask:0xf bank_mask:0xf
	v_mov_b32_dpp v191, v191 row_shr:1 row_mask:0xf bank_mask:0xf
	v_cvt_f32_i32_e32 v172, v118
	v_pk_mul_f32 v[160:161], v[128:129], v[160:161] op_sel:[1,0]
	s_waitcnt vmcnt(0)
	v_pk_mul_f32 v[172:173], v[130:131], v[172:173] op_sel_hi:[0,1]
	s_waitcnt vmcnt(1)
	v_max_f32_e32 v140, v140, v140
	v_max_f32_e32 v141, v141, v141
	v_max_f32_e32 v140, 0xda24260, v140
	v_max_f32_e32 v141, 0xda24260, v141
	v_pk_mul_f32 v[140:141], v[140:141], s[42:43] op_sel_hi:[1,0]
	s_waitcnt vmcnt(0)
	global_load_dwordx4 v[242:245], v[92:93], off offset:64
	global_load_dwordx4 v[246:249], v[88:89], off offset:64
	v_lshlrev_b32_e32 v227, 2, v80
	v_add_u32_e32 v227, 0x2c40, v227
	global_load_dword v220, v227, s[28:29]
	global_load_dword v237, v227, s[28:29] offset:4
	global_load_dword v241, v227, s[26:27]
	global_load_dword v227, v227, s[26:27] offset:4
	v_pk_add_f32 v[144:145], v[144:145], 0 neg_lo:[1,1] neg_hi:[1,1]
	s_nop 0
	v_div_scale_f32 v148, s[24:25], v140, v140, v144
	v_rcp_f32_e32 v149, v148
	s_nop 0
	v_fma_f32 v152, -v148, v149, 1.0
	v_fmac_f32_e32 v149, v152, v149
	v_div_scale_f32 v152, vcc, v144, v140, v144
	v_mul_f32_e32 v153, v152, v149
	v_fma_f32 v156, -v148, v153, v152
	v_fmac_f32_e32 v153, v156, v149
	v_fma_f32 v148, -v148, v153, v152
	v_div_fmas_f32 v148, v148, v149, v153
	v_div_fixup_f32 v200, v148, v140, v144
	v_div_scale_f32 v140, s[24:25], v141, v141, v145
	v_rcp_f32_e32 v144, v140
	v_cvt_f32_i32_e32 v153, v99
	v_cvt_f32_i32_e32 v156, v126
	v_fma_f32 v148, -v140, v144, 1.0
	v_fmac_f32_e32 v144, v148, v144
	v_div_scale_f32 v148, vcc, v145, v141, v145
	v_mul_f32_e32 v149, v148, v144
	v_fma_f32 v152, -v140, v149, v148
	v_fmac_f32_e32 v149, v152, v144
	v_fma_f32 v140, -v140, v149, v148
	v_div_fmas_f32 v140, v140, v144, v149
	v_div_fixup_f32 v201, v140, v141, v145
	v_cvt_f32_i32_e32 v141, v111
	v_cvt_f32_i32_e32 v140, v110
	v_cvt_f32_i32_e32 v145, v107
	v_cvt_f32_i32_e32 v144, v106
	v_cvt_f32_i32_e32 v149, v103
	v_cvt_f32_i32_e32 v148, v102
	v_cvt_f32_i32_e32 v152, v98
	v_pk_mul_f32 v[140:141], v[132:133], v[140:141] op_sel_hi:[0,1]
	v_pk_mul_f32 v[144:145], v[132:133], v[144:145] op_sel:[1,0]
	v_pk_fma_f32 v[198:199], v[146:147], v[140:141], v[150:151]
	v_pk_mul_f32 v[148:149], v[134:135], v[148:149] op_sel_hi:[0,1]
	v_cndmask_b32_e64 v195, v145, v201, s[8:9]
	v_cndmask_b32_e64 v194, v144, v200, s[8:9]
	v_pk_fma_f32 v[190:191], v[138:139], v[190:191], v[198:199]
	v_pk_mul_f32 v[152:153], v[184:185], v[152:153] op_sel_hi:[0,1]
	v_mov_b32_e32 v192, v140
	v_mov_b32_e32 v193, v141
	v_pk_fma_f32 v[190:191], v[142:143], v[194:195], v[190:191]
	v_cndmask_b32_e64 v141, v141, v201, s[10:11]
	v_cndmask_b32_e64 v140, v140, v200, s[10:11]
	v_pk_fma_f32 v[194:195], v[146:147], v[144:145], v[150:151]
	v_pk_fma_f32 v[198:199], v[146:147], v[148:149], v[150:151]
	v_pk_mul_f32 v[156:157], v[128:129], v[156:157] op_sel_hi:[0,1]
	v_pk_fma_f32 v[140:141], v[138:139], v[140:141], v[194:195]
	v_cndmask_b32_e64 v195, v153, v201, s[12:13]
	v_cndmask_b32_e64 v194, v152, v200, s[12:13]
	v_pk_fma_f32 v[144:145], v[138:139], v[144:145], v[198:199]
	v_pk_fma_f32 v[140:141], v[142:143], v[148:149], v[140:141]
	v_pk_fma_f32 v[144:145], v[142:143], v[194:195], v[144:145]
	v_cndmask_b32_e64 v149, v149, v201, s[14:15]
	v_cndmask_b32_e64 v148, v148, v200, s[14:15]
	v_pk_fma_f32 v[194:195], v[146:147], v[152:153], v[150:151]
	v_pk_fma_f32 v[198:199], v[146:147], v[156:157], v[150:151]
	v_pk_fma_f32 v[148:149], v[138:139], v[148:149], v[194:195]
	v_cndmask_b32_e64 v195, v161, v201, s[22:23]
	v_cndmask_b32_e64 v194, v160, v200, s[22:23]
	v_pk_fma_f32 v[152:153], v[138:139], v[152:153], v[198:199]
	v_pk_fma_f32 v[148:149], v[142:143], v[156:157], v[148:149]
	v_pk_fma_f32 v[152:153], v[142:143], v[194:195], v[152:153]
	v_cndmask_b32_e64 v157, v157, v201, s[20:21]
	v_cndmask_b32_e64 v156, v156, v200, s[20:21]
	v_pk_fma_f32 v[194:195], v[146:147], v[160:161], v[150:151]
	v_pk_fma_f32 v[198:199], v[146:147], v[172:173], v[150:151]
	v_pk_fma_f32 v[156:157], v[138:139], v[156:157], v[194:195]
	v_pk_fma_f32 v[146:147], v[146:147], v[188:189], v[150:151]
	v_pk_fma_f32 v[156:157], v[142:143], v[172:173], v[156:157]
	v_cndmask_b32_e64 v173, v173, v201, s[16:17]
	v_cndmask_b32_e64 v172, v172, v200, s[16:17]
	v_mov_b32_dpp v192, v192 row_shl:1 row_mask:0xf bank_mask:0xf
	v_mov_b32_dpp v193, v193 row_shl:1 row_mask:0xf bank_mask:0xf
	v_pk_fma_f32 v[160:161], v[138:139], v[160:161], v[198:199]
	v_pk_fma_f32 v[138:139], v[138:139], v[172:173], v[146:147]
	v_cndmask_b32_e64 v195, v189, v201, s[18:19]
	v_cndmask_b32_e64 v194, v188, v200, s[18:19]
	v_pk_fma_f32 v[146:147], v[142:143], v[192:193], v[138:139]
	v_and_b32_e32 v139, 0x7fffffff, v191
	v_and_b32_e32 v138, 0x7fffffff, v190
	v_pk_fma_f32 v[160:161], v[142:143], v[194:195], v[160:161]
	v_pk_fma_f32 v[142:143], v[138:139], s[80:81], v[136:137] op_sel_hi:[1,0,0]
	v_and_b32_e32 v199, 0x7fffffff, v141
	v_pk_fma_f32 v[142:143], v[138:139], v[142:143], s[84:85] op_sel_hi:[1,1,0]
	v_and_b32_e32 v198, 0x7fffffff, v140
	v_pk_fma_f32 v[142:143], v[138:139], v[142:143], s[86:87] op_sel_hi:[1,1,0]
	v_pk_fma_f32 v[200:201], v[198:199], s[80:81], v[136:137] op_sel_hi:[1,0,0]
	v_pk_fma_f32 v[142:143], v[138:139], v[142:143], s[82:83] op_sel_hi:[1,1,0]
	v_pk_fma_f32 v[200:201], v[198:199], v[200:201], s[84:85] op_sel_hi:[1,1,0]
	v_pk_fma_f32 v[142:143], v[138:139], v[142:143], s[94:95] op_sel_hi:[1,1,0]
	v_pk_fma_f32 v[200:201], v[198:199], v[200:201], s[86:87] op_sel_hi:[1,1,0]
	v_pk_fma_f32 v[142:143], v[138:139], v[142:143], s[92:93] op_sel_hi:[1,1,0]
	v_and_b32_e32 v195, 0x7fffffff, v145
	v_pk_mul_f32 v[142:143], v[142:143], v[142:143]
	v_and_b32_e32 v194, 0x7fffffff, v144
	v_pk_fma_f32 v[200:201], v[198:199], v[200:201], s[82:83] op_sel_hi:[1,1,0]
	v_pk_mul_f32 v[142:143], v[142:143], v[142:143]
	v_pk_fma_f32 v[204:205], v[194:195], s[80:81], v[136:137] op_sel_hi:[1,0,0]
	v_pk_fma_f32 v[200:201], v[198:199], v[200:201], s[94:95] op_sel_hi:[1,1,0]
	v_pk_mul_f32 v[142:143], v[142:143], v[142:143]
	v_pk_fma_f32 v[204:205], v[194:195], v[204:205], s[84:85] op_sel_hi:[1,1,0]
	v_pk_fma_f32 v[200:201], v[198:199], v[200:201], s[92:93] op_sel_hi:[1,1,0]
	v_pk_mul_f32 v[142:143], v[142:143], v[142:143]
	v_pk_fma_f32 v[204:205], v[194:195], v[204:205], s[86:87] op_sel_hi:[1,1,0]
	v_pk_mul_f32 v[200:201], v[200:201], v[200:201]
	v_rcp_f32_e32 v142, v142
	v_rcp_f32_e32 v143, v143
	v_and_b32_e32 v193, 0x7fffffff, v149
	v_and_b32_e32 v192, 0x7fffffff, v148
	v_pk_fma_f32 v[204:205], v[194:195], v[204:205], s[82:83] op_sel_hi:[1,1,0]
	v_pk_mul_f32 v[200:201], v[200:201], v[200:201]
	v_pk_fma_f32 v[206:207], v[192:193], s[80:81], v[136:137] op_sel_hi:[1,0,0]
	v_pk_fma_f32 v[204:205], v[194:195], v[204:205], s[94:95] op_sel_hi:[1,1,0]
	v_pk_mul_f32 v[200:201], v[200:201], v[200:201]
	v_pk_fma_f32 v[206:207], v[192:193], v[206:207], s[84:85] op_sel_hi:[1,1,0]
	v_pk_fma_f32 v[204:205], v[194:195], v[204:205], s[92:93] op_sel_hi:[1,1,0]
	v_pk_mul_f32 v[200:201], v[200:201], v[200:201]
	v_max_f32_e32 v191, 0, v191
	v_max_f32_e32 v190, 0, v190
	v_pk_fma_f32 v[206:207], v[192:193], v[206:207], s[86:87] op_sel_hi:[1,1,0]
	v_pk_mul_f32 v[204:205], v[204:205], v[204:205]
	v_pk_fma_f32 v[138:139], v[138:139], v[142:143], v[190:191] neg_lo:[1,0,0] neg_hi:[1,0,0]
	v_rcp_f32_e32 v142, v200
	v_rcp_f32_e32 v143, v201
	v_pk_fma_f32 v[206:207], v[192:193], v[206:207], s[82:83] op_sel_hi:[1,1,0]
	v_pk_mul_f32 v[204:205], v[204:205], v[204:205]
	v_pk_fma_f32 v[206:207], v[192:193], v[206:207], s[94:95] op_sel_hi:[1,1,0]
	v_pk_mul_f32 v[204:205], v[204:205], v[204:205]
	v_pk_fma_f32 v[206:207], v[192:193], v[206:207], s[92:93] op_sel_hi:[1,1,0]
	v_pk_mul_f32 v[204:205], v[204:205], v[204:205]
	v_max_f32_e32 v141, 0, v141
	v_max_f32_e32 v140, 0, v140
	v_pk_mul_f32 v[206:207], v[206:207], v[206:207]
	v_pk_fma_f32 v[142:143], v[198:199], v[142:143], v[140:141] neg_lo:[1,0,0] neg_hi:[1,0,0]
	v_rcp_f32_e32 v140, v204
	v_rcp_f32_e32 v141, v205
	v_pk_mul_f32 v[206:207], v[206:207], v[206:207]
	v_max_f32_e32 v145, 0, v145
	v_pk_mul_f32 v[206:207], v[206:207], v[206:207]
	v_max_f32_e32 v144, 0, v144
	v_pk_mul_f32 v[206:207], v[206:207], v[206:207]
	v_pk_fma_f32 v[140:141], v[194:195], v[140:141], v[144:145] neg_lo:[1,0,0] neg_hi:[1,0,0]
	v_rcp_f32_e32 v144, v206
	v_rcp_f32_e32 v145, v207
	v_max_f32_e32 v149, 0, v149
	v_max_f32_e32 v148, 0, v148
	v_and_b32_e32 v173, 0x7fffffff, v147
	v_pk_fma_f32 v[144:145], v[192:193], v[144:145], v[148:149] neg_lo:[1,0,0] neg_hi:[1,0,0]
	v_and_b32_e32 v149, 0x7fffffff, v153
	v_and_b32_e32 v148, 0x7fffffff, v152
	v_and_b32_e32 v172, 0x7fffffff, v146
	v_and_b32_e32 v151, 0x7fffffff, v161
	v_and_b32_e32 v150, 0x7fffffff, v160
	v_and_b32_e32 v189, 0x7fffffff, v157
	v_and_b32_e32 v188, 0x7fffffff, v156
	v_pk_fma_f32 v[190:191], v[148:149], s[80:81], v[136:137] op_sel_hi:[1,0,0]
	v_pk_fma_f32 v[192:193], v[188:189], s[80:81], v[136:137] op_sel_hi:[1,0,0]
	v_pk_fma_f32 v[194:195], v[150:151], s[80:81], v[136:137] op_sel_hi:[1,0,0]
	v_pk_fma_f32 v[136:137], v[172:173], s[80:81], v[136:137] op_sel_hi:[1,0,0]
	v_pk_fma_f32 v[190:191], v[148:149], v[190:191], s[84:85] op_sel_hi:[1,1,0]
	v_pk_fma_f32 v[136:137], v[172:173], v[136:137], s[84:85] op_sel_hi:[1,1,0]
	v_pk_fma_f32 v[190:191], v[148:149], v[190:191], s[86:87] op_sel_hi:[1,1,0]
	v_pk_fma_f32 v[136:137], v[172:173], v[136:137], s[86:87] op_sel_hi:[1,1,0]
	v_pk_fma_f32 v[190:191], v[148:149], v[190:191], s[82:83] op_sel_hi:[1,1,0]
	v_pk_fma_f32 v[136:137], v[172:173], v[136:137], s[82:83] op_sel_hi:[1,1,0]
	v_pk_fma_f32 v[190:191], v[148:149], v[190:191], s[94:95] op_sel_hi:[1,1,0]
	v_pk_fma_f32 v[192:193], v[188:189], v[192:193], s[84:85] op_sel_hi:[1,1,0]
	v_pk_fma_f32 v[136:137], v[172:173], v[136:137], s[94:95] op_sel_hi:[1,1,0]
	v_pk_fma_f32 v[190:191], v[148:149], v[190:191], s[92:93] op_sel_hi:[1,1,0]
	v_pk_fma_f32 v[192:193], v[188:189], v[192:193], s[86:87] op_sel_hi:[1,1,0]
	v_pk_fma_f32 v[136:137], v[172:173], v[136:137], s[92:93] op_sel_hi:[1,1,0]
	v_pk_mul_f32 v[190:191], v[190:191], v[190:191]
	v_pk_fma_f32 v[192:193], v[188:189], v[192:193], s[82:83] op_sel_hi:[1,1,0]
	v_pk_mul_f32 v[136:137], v[136:137], v[136:137]
	v_pk_mul_f32 v[190:191], v[190:191], v[190:191]
	v_pk_fma_f32 v[192:193], v[188:189], v[192:193], s[94:95] op_sel_hi:[1,1,0]
	v_pk_mul_f32 v[136:137], v[136:137], v[136:137]
	v_pk_mul_f32 v[190:191], v[190:191], v[190:191]
	v_pk_fma_f32 v[194:195], v[150:151], v[194:195], s[84:85] op_sel_hi:[1,1,0]
	v_pk_fma_f32 v[192:193], v[188:189], v[192:193], s[92:93] op_sel_hi:[1,1,0]
	v_pk_mul_f32 v[136:137], v[136:137], v[136:137]
	v_pk_mul_f32 v[190:191], v[190:191], v[190:191]
	v_pk_fma_f32 v[194:195], v[150:151], v[194:195], s[86:87] op_sel_hi:[1,1,0]
	v_pk_mul_f32 v[192:193], v[192:193], v[192:193]
	v_pk_mul_f32 v[198:199], v[136:137], v[136:137]
	v_rcp_f32_e32 v136, v190
	v_rcp_f32_e32 v137, v191
	v_pk_fma_f32 v[194:195], v[150:151], v[194:195], s[82:83] op_sel_hi:[1,1,0]
	v_pk_mul_f32 v[192:193], v[192:193], v[192:193]
	v_pk_fma_f32 v[194:195], v[150:151], v[194:195], s[94:95] op_sel_hi:[1,1,0]
	v_pk_mul_f32 v[192:193], v[192:193], v[192:193]
	v_pk_fma_f32 v[194:195], v[150:151], v[194:195], s[92:93] op_sel_hi:[1,1,0]
	v_pk_mul_f32 v[192:193], v[192:193], v[192:193]
	v_max_f32_e32 v153, 0, v153
	v_max_f32_e32 v152, 0, v152
	v_pk_mul_f32 v[194:195], v[194:195], v[194:195]
	v_pk_fma_f32 v[148:149], v[148:149], v[136:137], v[152:153] neg_lo:[1,0,0] neg_hi:[1,0,0]
	v_rcp_f32_e32 v136, v192
	v_rcp_f32_e32 v137, v193
	v_pk_mul_f32 v[194:195], v[194:195], v[194:195]
	v_max_f32_e32 v153, 0, v157
	v_pk_mul_f32 v[194:195], v[194:195], v[194:195]
	v_max_f32_e32 v152, 0, v156
	v_pk_mul_f32 v[194:195], v[194:195], v[194:195]
	v_pk_fma_f32 v[136:137], v[188:189], v[136:137], v[152:153] neg_lo:[1,0,0] neg_hi:[1,0,0]
	v_rcp_f32_e32 v152, v194
	v_rcp_f32_e32 v153, v195
	v_max_f32_e32 v157, 0, v161
	v_max_f32_e32 v156, 0, v160
	v_max_f32_e32 v147, 0, v147
	v_pk_fma_f32 v[150:151], v[150:151], v[152:153], v[156:157] neg_lo:[1,0,0] neg_hi:[1,0,0]
	v_rcp_f32_e32 v152, v198
	v_rcp_f32_e32 v153, v199
	v_max_f32_e32 v146, 0, v146
	v_pk_add_f32 v[156:157], v[170:171], 0 neg_lo:[1,1] neg_hi:[1,1]
	v_cvt_f32_i32_e32 v191, v83
	v_pk_fma_f32 v[146:147], v[172:173], v[152:153], v[146:147] neg_lo:[1,0,0] neg_hi:[1,0,0]
	v_max_f32_e32 v152, v166, v166
	v_max_f32_e32 v153, v167, v167
	v_max_f32_e32 v152, 0xda24260, v152
	v_max_f32_e32 v153, 0xda24260, v153
	v_pk_mul_f32 v[152:153], v[152:153], s[42:43] op_sel_hi:[1,0]
	v_cvt_f32_i32_e32 v190, v82
	v_div_scale_f32 v160, s[24:25], v152, v152, v156
	v_rcp_f32_e32 v161, v160
	v_pk_mul_f32 v[190:191], v[84:85], v[190:191] op_sel_hi:[0,1]
	v_mov_b32_e32 v192, v190
	v_mov_b32_e32 v193, v191
	v_fma_f32 v166, -v160, v161, 1.0
	v_fmac_f32_e32 v161, v166, v161
	v_div_scale_f32 v166, vcc, v156, v152, v156
	v_mul_f32_e32 v167, v166, v161
	v_fma_f32 v170, -v160, v167, v166
	v_fmac_f32_e32 v167, v170, v161
	v_fma_f32 v160, -v160, v167, v166
	v_div_fmas_f32 v160, v160, v161, v167
	v_div_fixup_f32 v203, v160, v152, v156
	v_div_scale_f32 v152, s[24:25], v153, v153, v157
	v_rcp_f32_e32 v156, v152
	v_mov_b32_dpp v192, v192 row_shr:1 row_mask:0xf bank_mask:0xf
	v_mov_b32_dpp v193, v193 row_shr:1 row_mask:0xf bank_mask:0xf
	v_cvt_f32_i32_e32 v167, v67
	v_fma_f32 v160, -v152, v156, 1.0
	v_fmac_f32_e32 v156, v160, v156
	v_div_scale_f32 v160, vcc, v157, v153, v157
	v_mul_f32_e32 v161, v160, v156
	v_fma_f32 v166, -v152, v161, v160
	v_fmac_f32_e32 v161, v166, v156
	v_fma_f32 v152, -v152, v161, v160
	v_div_fmas_f32 v152, v152, v156, v161
	v_div_fixup_f32 v204, v152, v153, v157
	v_cvt_f32_i32_e32 v153, v79
	v_cvt_f32_i32_e32 v152, v78
	v_cvt_f32_i32_e32 v157, v75
	v_cvt_f32_i32_e32 v156, v74
	v_cvt_f32_i32_e32 v161, v71
	v_pk_mul_f32 v[152:153], v[132:133], v[152:153] op_sel_hi:[0,1]
	v_pk_fma_f32 v[200:201], v[158:159], v[152:153], v[162:163]
	v_pk_mul_f32 v[156:157], v[132:133], v[156:157] op_sel:[1,0]
	v_cvt_f32_i32_e32 v160, v70
	v_cndmask_b32_e64 v199, v157, v204, s[8:9]
	v_cndmask_b32_e64 v198, v156, v203, s[8:9]
	v_pk_fma_f32 v[192:193], v[174:175], v[192:193], v[200:201]
	v_cvt_f32_i32_e32 v166, v66
	v_pk_fma_f32 v[192:193], v[154:155], v[198:199], v[192:193]
	v_mov_b32_e32 v194, v152
	v_pk_mul_f32 v[138:139], v[192:193], v[138:139]
	v_mov_b32_e32 v195, v153
	v_cvt_pk_fp8_f32 v197, v138, v139 op_sel:[0,0,1]
	s_nop 0
	v_cndmask_b32_e64 v139, v153, v204, s[10:11]
	v_cndmask_b32_e64 v138, v152, v203, s[10:11]
	v_pk_fma_f32 v[152:153], v[158:159], v[156:157], v[162:163]
	v_pk_mul_f32 v[160:161], v[134:135], v[160:161] op_sel_hi:[0,1]
	v_pk_fma_f32 v[138:139], v[174:175], v[138:139], v[152:153]
	v_pk_mul_f32 v[166:167], v[184:185], v[166:167] op_sel_hi:[0,1]
	v_pk_fma_f32 v[138:139], v[154:155], v[160:161], v[138:139]
	v_cvt_f32_i32_e32 v171, v95
	v_pk_mul_f32 v[138:139], v[138:139], v[142:143]
	v_pk_fma_f32 v[142:143], v[158:159], v[160:161], v[162:163]
	v_cvt_f32_i32_e32 v170, v94
	v_cvt_pk_fp8_f32 v187, v138, v139 op_sel:[0,0,1]
	s_nop 0
	v_cndmask_b32_e64 v139, v167, v204, s[12:13]
	v_cndmask_b32_e64 v138, v166, v203, s[12:13]
	v_pk_fma_f32 v[142:143], v[174:175], v[156:157], v[142:143]
	v_cvt_f32_i32_e32 v173, v91
	v_pk_fma_f32 v[138:139], v[154:155], v[138:139], v[142:143]
	v_cvt_f32_i32_e32 v172, v90
	v_pk_mul_f32 v[138:139], v[138:139], v[140:141]
	v_pk_fma_f32 v[140:141], v[158:159], v[166:167], v[162:163]
	v_cvt_pk_fp8_f32 v186, v138, v139 op_sel:[0,0,1]
	s_nop 0
	v_cndmask_b32_e64 v139, v161, v204, s[14:15]
	v_cndmask_b32_e64 v138, v160, v203, s[14:15]
	v_pk_mul_f32 v[170:171], v[128:129], v[170:171] op_sel_hi:[0,1]
	v_pk_fma_f32 v[138:139], v[174:175], v[138:139], v[140:141]
	v_pk_mul_f32 v[172:173], v[128:129], v[172:173] op_sel:[1,0]
	v_pk_fma_f32 v[138:139], v[154:155], v[170:171], v[138:139]
	v_pk_fma_f32 v[140:141], v[158:159], v[170:171], v[162:163]
	v_pk_mul_f32 v[138:139], v[138:139], v[144:145]
	v_cvt_f32_i32_e32 v189, v87
	v_cvt_f32_i32_e32 v188, v86
	v_cvt_pk_fp8_f32 v169, v138, v139 op_sel:[0,0,1]
	s_nop 0
	v_cndmask_b32_e64 v139, v173, v204, s[22:23]
	v_cndmask_b32_e64 v138, v172, v203, s[22:23]
	v_pk_fma_f32 v[140:141], v[174:175], v[166:167], v[140:141]
	v_pk_mul_f32 v[188:189], v[130:131], v[188:189] op_sel_hi:[0,1]
	v_pk_fma_f32 v[138:139], v[154:155], v[138:139], v[140:141]
	v_pk_fma_f32 v[140:141], v[158:159], v[172:173], v[162:163]
	v_pk_mul_f32 v[138:139], v[138:139], v[148:149]
	v_add_u32_e32 v84, -1, v185
	v_cvt_pk_fp8_f32 v168, v138, v139 op_sel:[0,0,1]
	s_nop 0
	v_cndmask_b32_e64 v139, v171, v204, s[20:21]
	v_cndmask_b32_e64 v138, v170, v203, s[20:21]
	v_pk_fma_f32 v[138:139], v[174:175], v[138:139], v[140:141]
	v_mov_b32_dpp v194, v194 row_shl:1 row_mask:0xf bank_mask:0xf
	v_pk_fma_f32 v[138:139], v[154:155], v[188:189], v[138:139]
	v_mov_b32_dpp v195, v195 row_shl:1 row_mask:0xf bank_mask:0xf
	v_pk_mul_f32 v[136:137], v[138:139], v[136:137]
	v_pk_fma_f32 v[138:139], v[158:159], v[188:189], v[162:163]
	v_cvt_pk_fp8_f32 v165, v136, v137 op_sel:[0,0,1]
	s_nop 0
	v_cndmask_b32_e64 v137, v191, v204, s[18:19]
	v_cndmask_b32_e64 v136, v190, v203, s[18:19]
	v_pk_fma_f32 v[138:139], v[174:175], v[172:173], v[138:139]
	v_cmp_gt_u32_e32 vcc, s87, v84
	v_pk_fma_f32 v[136:137], v[154:155], v[136:137], v[138:139]
	v_pk_fma_f32 v[138:139], v[158:159], v[190:191], v[162:163]
	v_pk_mul_f32 v[136:137], v[136:137], v[150:151]
	v_cmp_gt_i32_e64 s[24:25], s81, v85
	v_cvt_pk_fp8_f32 v164, v136, v137 op_sel:[0,0,1]
	s_nop 0
	v_cndmask_b32_e64 v137, v189, v204, s[16:17]
	v_cndmask_b32_e64 v136, v188, v203, s[16:17]
	v_pk_fma_f32 v[136:137], v[174:175], v[136:137], v[138:139]
	s_and_b64 s[42:43], vcc, s[24:25]
	v_pk_fma_f32 v[136:137], v[154:155], v[194:195], v[136:137]
	s_nop 0
	v_pk_mul_f32 v[136:137], v[136:137], v[146:147]
	s_nop 0
	v_cvt_pk_fp8_f32 v81, v136, v137 op_sel:[0,0,1]
	s_nop 0
	s_waitcnt vmcnt(0)
	s_and_saveexec_b64 s[24:25], s[42:43]
	s_cbranch_execz .LBB0_662
	s_movk_i32 s3, 0xb00
	v_mad_u64_u32 v[136:137], s[44:45], v85, s3, v[80:81]
	buffer_store_dword v197, v136, s[88:91], 0 offen

.LBB0_676:
	s_or_b64 exec, exec, s[56:57]
	v_add_u32_e32 v152, 0xb10, v80
	v_ashrrev_i32_e32 v153, 31, v152
	v_lshlrev_b64 v[152:153], 2, v[152:153]
	v_lshl_add_u64 v[154:155], s[28:29], 0, v[152:153]
	ds_read2_b64 v[136:139], v196 offset0:8 offset1:9
	ds_read2_b64 v[144:147], v196 offset0:72 offset1:73
	ds_read2_b64 v[140:143], v196 offset0:136 offset1:137
	ds_read2_b64 v[148:151], v196 offset0:200 offset1:201
	v_mov_b32_e32 v154, v220
	v_mov_b32_e32 v155, v237
	v_mov_b32_e32 v152, v241
	v_mov_b32_e32 v153, v227
	s_mov_b32 s30, 0x3c010204
	v_mov_b32_e32 v190, v132
	v_mov_b32_e32 v191, v132
	v_mov_b32_e32 v132, v133
	v_cvt_f32_i32_e32 v163, v49
	v_cvt_f32_i32_e32 v162, v48
	v_mov_b32_e32 v188, v134
	v_mov_b32_e32 v189, v134
	v_mov_b32_e32 v184, v130
	v_mov_b32_e32 v185, v130
	v_mov_b32_e32 v130, v131
	v_pk_mul_f32 v[166:167], v[130:131], v[162:163]
	v_mov_b32_e32 v186, v128
	v_mov_b32_e32 v187, v128
	v_mov_b32_e32 v162, v166
	v_mov_b32_e32 v163, v167
	v_mov_b32_e32 v134, v135
	v_mov_b32_dpp v162, v162 row_shr:1 row_mask:0xf bank_mask:0xf
	v_mov_b32_dpp v163, v163 row_shr:1 row_mask:0xf bank_mask:0xf
	v_mov_b32_e32 v128, v129
	v_cvt_f32_i32_e32 v161, v53
	v_cvt_f32_i32_e32 v160, v52
	v_add_u32_e32 v84, 16, v80
	v_add_u32_e32 v80, 0xb12, v80
	v_pk_mul_f32 v[160:161], v[184:185], v[160:161]
	v_lshlrev_b32_e32 v227, 2, v80
	v_max_f32_e32 v81, v154, v154
	v_max_f32_e32 v154, 0xda24260, v81
	v_max_f32_e32 v81, v155, v155
	v_max_f32_e32 v155, 0xda24260, v81
	global_load_dword v176, v227, s[28:29]
	global_load_dword v237, v227, s[28:29] offset:4
	global_load_dword v241, v227, s[26:27]
	global_load_dword v227, v227, s[26:27] offset:4
	v_pk_add_f32 v[152:153], v[152:153], 0 neg_lo:[1,1] neg_hi:[1,1]
	v_pk_mul_f32 v[154:155], v[154:155], s[30:31] op_sel_hi:[1,0]
	s_nop 0
	v_div_scale_f32 v81, s[56:57], v154, v154, v152
	v_rcp_f32_e32 v156, v81
	s_nop 0
	v_fma_f32 v157, -v81, v156, 1.0
	v_fmac_f32_e32 v156, v157, v156
	v_div_scale_f32 v157, vcc, v152, v154, v152
	v_mul_f32_e32 v158, v157, v156
	v_fma_f32 v159, -v81, v158, v157
	v_fmac_f32_e32 v158, v159, v156
	v_fma_f32 v81, -v81, v158, v157
	v_div_fmas_f32 v81, v81, v156, v158
	v_div_fixup_f32 v81, v81, v154, v152
	v_div_scale_f32 v152, s[56:57], v155, v155, v153
	v_rcp_f32_e32 v154, v152
	s_mov_b32 s56, 0x3856241d
	v_fma_f32 v156, -v152, v154, 1.0
	v_fmac_f32_e32 v154, v156, v154
	v_div_scale_f32 v156, vcc, v153, v155, v153
	v_mul_f32_e32 v157, v156, v154
	v_fma_f32 v158, -v152, v157, v156
	v_fmac_f32_e32 v157, v158, v154
	v_fma_f32 v152, -v152, v157, v156
	v_div_fmas_f32 v152, v152, v154, v157
	v_div_fixup_f32 v170, v152, v155, v153
	v_cvt_f32_i32_e32 v153, v45
	v_cvt_f32_i32_e32 v152, v44
	v_cvt_f32_i32_e32 v157, v61
	v_cvt_f32_i32_e32 v156, v60
	v_pk_mul_f32 v[164:165], v[190:191], v[152:153]
	v_cvt_f32_i32_e32 v153, v41
	v_cvt_f32_i32_e32 v152, v40
	v_pk_mul_f32 v[158:159], v[186:187], v[156:157]
	v_cvt_f32_i32_e32 v157, v57
	v_cvt_f32_i32_e32 v156, v56
	v_pk_mul_f32 v[172:173], v[132:133], v[152:153]
	v_cvt_f32_i32_e32 v153, v37
	v_cvt_f32_i32_e32 v152, v36
	s_waitcnt lgkmcnt(0)
	v_pk_fma_f32 v[192:193], v[144:145], v[164:165], v[148:149]
	v_cndmask_b32_e64 v175, v173, v170, s[8:9]
	v_cndmask_b32_e64 v174, v172, v81, s[8:9]
	v_pk_mul_f32 v[154:155], v[188:189], v[152:153]
	v_cvt_f32_i32_e32 v153, v33
	v_cvt_f32_i32_e32 v152, v32
	v_pk_fma_f32 v[162:163], v[136:137], v[162:163], v[192:193]
	v_mov_b32_e32 v168, v164
	v_mov_b32_e32 v169, v165
	v_pk_mul_f32 v[152:153], v[134:135], v[152:153]
	v_pk_fma_f32 v[162:163], v[140:141], v[174:175], v[162:163]
	v_cndmask_b32_e64 v165, v165, v170, s[10:11]
	v_cndmask_b32_e64 v164, v164, v81, s[10:11]
	v_pk_fma_f32 v[174:175], v[144:145], v[172:173], v[148:149]
	v_pk_fma_f32 v[192:193], v[144:145], v[154:155], v[148:149]
	v_pk_fma_f32 v[164:165], v[136:137], v[164:165], v[174:175]
	v_cndmask_b32_e64 v175, v153, v170, s[12:13]
	v_cndmask_b32_e64 v174, v152, v81, s[12:13]
	v_pk_fma_f32 v[172:173], v[136:137], v[172:173], v[192:193]
	v_pk_mul_f32 v[156:157], v[128:129], v[156:157]
	v_pk_fma_f32 v[164:165], v[140:141], v[154:155], v[164:165]
	v_pk_fma_f32 v[172:173], v[140:141], v[174:175], v[172:173]
	v_cndmask_b32_e64 v155, v155, v170, s[14:15]
	v_cndmask_b32_e64 v154, v154, v81, s[14:15]
	v_pk_fma_f32 v[174:175], v[144:145], v[152:153], v[148:149]
	v_pk_fma_f32 v[192:193], v[144:145], v[158:159], v[148:149]
	v_pk_fma_f32 v[154:155], v[136:137], v[154:155], v[174:175]
	v_cndmask_b32_e64 v175, v157, v170, s[22:23]
	v_cndmask_b32_e64 v174, v156, v81, s[22:23]
	v_pk_fma_f32 v[152:153], v[136:137], v[152:153], v[192:193]
	v_pk_fma_f32 v[154:155], v[140:141], v[158:159], v[154:155]
	v_pk_fma_f32 v[152:153], v[140:141], v[174:175], v[152:153]
	v_cndmask_b32_e64 v159, v159, v170, s[20:21]
	v_cndmask_b32_e64 v158, v158, v81, s[20:21]
	v_pk_fma_f32 v[174:175], v[144:145], v[156:157], v[148:149]
	v_pk_fma_f32 v[192:193], v[144:145], v[160:161], v[148:149]
	v_pk_fma_f32 v[158:159], v[136:137], v[158:159], v[174:175]
	v_pk_fma_f32 v[144:145], v[144:145], v[166:167], v[148:149]
	v_pk_fma_f32 v[158:159], v[140:141], v[160:161], v[158:159]
	v_cndmask_b32_e64 v161, v161, v170, s[16:17]
	v_cndmask_b32_e64 v160, v160, v81, s[16:17]
	v_mov_b32_dpp v168, v168 row_shl:1 row_mask:0xf bank_mask:0xf
	v_mov_b32_dpp v169, v169 row_shl:1 row_mask:0xf bank_mask:0xf
	v_cndmask_b32_e64 v175, v167, v170, s[18:19]
	v_cndmask_b32_e64 v174, v166, v81, s[18:19]
	v_pk_fma_f32 v[156:157], v[136:137], v[156:157], v[192:193]
	v_pk_fma_f32 v[136:137], v[136:137], v[160:161], v[144:145]
	v_pk_fma_f32 v[156:157], v[140:141], v[174:175], v[156:157]
	v_pk_fma_f32 v[160:161], v[140:141], v[168:169], v[136:137]
	v_and_b32_e32 v141, 0x7fffffff, v163
	v_and_b32_e32 v140, 0x7fffffff, v162
	v_mov_b64_e32 v[136:137], s[56:57]
	v_pk_fma_f32 v[144:145], v[140:141], s[80:81], v[136:137] op_sel_hi:[1,0,0]
	v_and_b32_e32 v149, 0x7fffffff, v165
	v_pk_fma_f32 v[144:145], v[140:141], v[144:145], s[84:85] op_sel_hi:[1,1,0]
	v_and_b32_e32 v148, 0x7fffffff, v164
	v_pk_fma_f32 v[144:145], v[140:141], v[144:145], s[86:87] op_sel_hi:[1,1,0]
	v_pk_fma_f32 v[192:193], v[148:149], s[80:81], v[136:137] op_sel_hi:[1,0,0]
	v_pk_fma_f32 v[144:145], v[140:141], v[144:145], s[82:83] op_sel_hi:[1,1,0]
	v_pk_fma_f32 v[192:193], v[148:149], v[192:193], s[84:85] op_sel_hi:[1,1,0]
	v_pk_fma_f32 v[144:145], v[140:141], v[144:145], s[94:95] op_sel_hi:[1,1,0]
	v_pk_fma_f32 v[192:193], v[148:149], v[192:193], s[86:87] op_sel_hi:[1,1,0]
	v_pk_fma_f32 v[144:145], v[140:141], v[144:145], s[92:93] op_sel_hi:[1,1,0]
	v_and_b32_e32 v195, 0x7fffffff, v173
	v_pk_mul_f32 v[144:145], v[144:145], v[144:145]
	v_and_b32_e32 v194, 0x7fffffff, v172
	v_pk_fma_f32 v[192:193], v[148:149], v[192:193], s[82:83] op_sel_hi:[1,1,0]
	v_pk_mul_f32 v[144:145], v[144:145], v[144:145]
	v_pk_fma_f32 v[196:197], v[194:195], s[80:81], v[136:137] op_sel_hi:[1,0,0]
	v_pk_fma_f32 v[192:193], v[148:149], v[192:193], s[94:95] op_sel_hi:[1,1,0]
	v_pk_mul_f32 v[144:145], v[144:145], v[144:145]
	v_pk_fma_f32 v[196:197], v[194:195], v[196:197], s[84:85] op_sel_hi:[1,1,0]
	v_pk_fma_f32 v[192:193], v[148:149], v[192:193], s[92:93] op_sel_hi:[1,1,0]
	v_pk_mul_f32 v[144:145], v[144:145], v[144:145]
	v_pk_fma_f32 v[196:197], v[194:195], v[196:197], s[86:87] op_sel_hi:[1,1,0]
	v_pk_mul_f32 v[192:193], v[192:193], v[192:193]
	v_rcp_f32_e32 v144, v144
	v_rcp_f32_e32 v145, v145
	v_and_b32_e32 v175, 0x7fffffff, v155
	v_and_b32_e32 v174, 0x7fffffff, v154
	v_pk_fma_f32 v[196:197], v[194:195], v[196:197], s[82:83] op_sel_hi:[1,1,0]
	v_pk_mul_f32 v[192:193], v[192:193], v[192:193]
	v_pk_fma_f32 v[198:199], v[174:175], s[80:81], v[136:137] op_sel_hi:[1,0,0]
	v_pk_fma_f32 v[196:197], v[194:195], v[196:197], s[94:95] op_sel_hi:[1,1,0]
	v_pk_mul_f32 v[192:193], v[192:193], v[192:193]
	v_pk_fma_f32 v[198:199], v[174:175], v[198:199], s[84:85] op_sel_hi:[1,1,0]
	v_pk_fma_f32 v[196:197], v[194:195], v[196:197], s[92:93] op_sel_hi:[1,1,0]
	v_pk_mul_f32 v[200:201], v[192:193], v[192:193]
	v_max_f32_e32 v163, 0, v163
	v_max_f32_e32 v162, 0, v162
	v_pk_fma_f32 v[198:199], v[174:175], v[198:199], s[86:87] op_sel_hi:[1,1,0]
	v_pk_mul_f32 v[196:197], v[196:197], v[196:197]
	v_pk_fma_f32 v[192:193], v[140:141], v[144:145], v[162:163] neg_lo:[1,0,0] neg_hi:[1,0,0]
	v_rcp_f32_e32 v140, v200
	v_rcp_f32_e32 v141, v201
	v_pk_fma_f32 v[198:199], v[174:175], v[198:199], s[82:83] op_sel_hi:[1,1,0]
	v_pk_mul_f32 v[196:197], v[196:197], v[196:197]
	v_pk_fma_f32 v[198:199], v[174:175], v[198:199], s[94:95] op_sel_hi:[1,1,0]
	v_pk_mul_f32 v[196:197], v[196:197], v[196:197]
	v_pk_fma_f32 v[198:199], v[174:175], v[198:199], s[92:93] op_sel_hi:[1,1,0]
	v_pk_mul_f32 v[196:197], v[196:197], v[196:197]
	v_max_f32_e32 v145, 0, v165
	v_max_f32_e32 v144, 0, v164
	v_pk_mul_f32 v[198:199], v[198:199], v[198:199]
	v_pk_fma_f32 v[148:149], v[148:149], v[140:141], v[144:145] neg_lo:[1,0,0] neg_hi:[1,0,0]
	v_rcp_f32_e32 v140, v196
	v_rcp_f32_e32 v141, v197
	v_pk_mul_f32 v[198:199], v[198:199], v[198:199]
	v_max_f32_e32 v145, 0, v173
	v_pk_mul_f32 v[198:199], v[198:199], v[198:199]
	v_max_f32_e32 v144, 0, v172
	v_pk_mul_f32 v[198:199], v[198:199], v[198:199]
	v_pk_fma_f32 v[144:145], v[194:195], v[140:141], v[144:145] neg_lo:[1,0,0] neg_hi:[1,0,0]
	v_rcp_f32_e32 v140, v198
	v_rcp_f32_e32 v141, v199
	v_max_f32_e32 v155, 0, v155
	v_max_f32_e32 v154, 0, v154
	v_and_b32_e32 v171, 0x7fffffff, v159
	v_pk_fma_f32 v[140:141], v[174:175], v[140:141], v[154:155] neg_lo:[1,0,0] neg_hi:[1,0,0]
	v_and_b32_e32 v155, 0x7fffffff, v153
	v_and_b32_e32 v154, 0x7fffffff, v152
	v_pk_fma_f32 v[162:163], v[154:155], s[80:81], v[136:137] op_sel_hi:[1,0,0]
	v_and_b32_e32 v170, 0x7fffffff, v158
	v_pk_fma_f32 v[162:163], v[154:155], v[162:163], s[84:85] op_sel_hi:[1,1,0]
	v_pk_fma_f32 v[164:165], v[170:171], s[80:81], v[136:137] op_sel_hi:[1,0,0]
	v_pk_fma_f32 v[162:163], v[154:155], v[162:163], s[86:87] op_sel_hi:[1,1,0]
	v_pk_fma_f32 v[164:165], v[170:171], v[164:165], s[84:85] op_sel_hi:[1,1,0]
	v_pk_fma_f32 v[162:163], v[154:155], v[162:163], s[82:83] op_sel_hi:[1,1,0]
	v_pk_fma_f32 v[164:165], v[170:171], v[164:165], s[86:87] op_sel_hi:[1,1,0]
	v_pk_fma_f32 v[162:163], v[154:155], v[162:163], s[94:95] op_sel_hi:[1,1,0]
	v_and_b32_e32 v169, 0x7fffffff, v157
	v_pk_fma_f32 v[162:163], v[154:155], v[162:163], s[92:93] op_sel_hi:[1,1,0]
	v_and_b32_e32 v168, 0x7fffffff, v156
	v_pk_mul_f32 v[162:163], v[162:163], v[162:163]
	v_pk_fma_f32 v[164:165], v[170:171], v[164:165], s[82:83] op_sel_hi:[1,1,0]
	v_pk_mul_f32 v[162:163], v[162:163], v[162:163]
	v_pk_fma_f32 v[172:173], v[168:169], s[80:81], v[136:137] op_sel_hi:[1,0,0]
	v_pk_fma_f32 v[164:165], v[170:171], v[164:165], s[94:95] op_sel_hi:[1,1,0]
	v_pk_mul_f32 v[162:163], v[162:163], v[162:163]
	v_pk_fma_f32 v[172:173], v[168:169], v[172:173], s[84:85] op_sel_hi:[1,1,0]
	v_pk_fma_f32 v[164:165], v[170:171], v[164:165], s[92:93] op_sel_hi:[1,1,0]
	v_pk_mul_f32 v[162:163], v[162:163], v[162:163]
	v_pk_fma_f32 v[172:173], v[168:169], v[172:173], s[86:87] op_sel_hi:[1,1,0]
	v_pk_mul_f32 v[164:165], v[164:165], v[164:165]
	v_rcp_f32_e32 v162, v162
	v_rcp_f32_e32 v163, v163
	v_and_b32_e32 v167, 0x7fffffff, v161
	v_and_b32_e32 v166, 0x7fffffff, v160
	v_pk_fma_f32 v[172:173], v[168:169], v[172:173], s[82:83] op_sel_hi:[1,1,0]
	v_pk_mul_f32 v[164:165], v[164:165], v[164:165]
	v_pk_fma_f32 v[174:175], v[166:167], s[80:81], v[136:137] op_sel_hi:[1,0,0]
	v_pk_fma_f32 v[172:173], v[168:169], v[172:173], s[94:95] op_sel_hi:[1,1,0]
	v_pk_mul_f32 v[164:165], v[164:165], v[164:165]
	v_pk_fma_f32 v[174:175], v[166:167], v[174:175], s[84:85] op_sel_hi:[1,1,0]
	v_pk_fma_f32 v[172:173], v[168:169], v[172:173], s[92:93] op_sel_hi:[1,1,0]
	v_pk_mul_f32 v[164:165], v[164:165], v[164:165]
	v_max_f32_e32 v153, 0, v153
	v_max_f32_e32 v152, 0, v152
	v_pk_fma_f32 v[174:175], v[166:167], v[174:175], s[86:87] op_sel_hi:[1,1,0]
	v_pk_mul_f32 v[172:173], v[172:173], v[172:173]
	v_pk_fma_f32 v[200:201], v[154:155], v[162:163], v[152:153] neg_lo:[1,0,0] neg_hi:[1,0,0]
	v_rcp_f32_e32 v152, v164
	v_rcp_f32_e32 v153, v165
	v_pk_fma_f32 v[174:175], v[166:167], v[174:175], s[82:83] op_sel_hi:[1,1,0]
	v_pk_mul_f32 v[172:173], v[172:173], v[172:173]
	v_pk_fma_f32 v[174:175], v[166:167], v[174:175], s[94:95] op_sel_hi:[1,1,0]
	v_pk_mul_f32 v[172:173], v[172:173], v[172:173]
	v_pk_fma_f32 v[174:175], v[166:167], v[174:175], s[92:93] op_sel_hi:[1,1,0]
	v_pk_mul_f32 v[172:173], v[172:173], v[172:173]
	v_max_f32_e32 v155, 0, v159
	v_max_f32_e32 v154, 0, v158
	v_pk_mul_f32 v[174:175], v[174:175], v[174:175]
	v_pk_fma_f32 v[198:199], v[170:171], v[152:153], v[154:155] neg_lo:[1,0,0] neg_hi:[1,0,0]
	v_rcp_f32_e32 v152, v172
	v_rcp_f32_e32 v153, v173
	v_pk_mul_f32 v[174:175], v[174:175], v[174:175]
	v_max_f32_e32 v155, 0, v157
	v_pk_mul_f32 v[174:175], v[174:175], v[174:175]
	v_max_f32_e32 v154, 0, v156
	v_pk_mul_f32 v[174:175], v[174:175], v[174:175]
	v_pk_fma_f32 v[196:197], v[168:169], v[152:153], v[154:155] neg_lo:[1,0,0] neg_hi:[1,0,0]
	v_rcp_f32_e32 v152, v174
	v_rcp_f32_e32 v153, v175
	v_max_f32_e32 v155, 0, v161
	v_max_f32_e32 v154, 0, v160
	v_pk_fma_f32 v[194:195], v[166:167], v[152:153], v[154:155] neg_lo:[1,0,0] neg_hi:[1,0,0]
	ds_read2_b64 v[156:159], v202 offset0:72 offset1:73
	ds_read2_b64 v[152:155], v202 offset0:136 offset1:137
	ds_read2_b64 v[160:163], v202 offset0:200 offset1:201
	v_mov_b64_e32 v[164:165], v[242:243]
	v_mov_b64_e32 v[166:167], v[244:245]
	v_mov_b64_e32 v[168:169], v[246:247]
	v_mov_b64_e32 v[170:171], v[248:249]
	ds_read2_b64 v[172:175], v202 offset0:8 offset1:9
	v_max_f32_e32 v81, v164, v164
	v_max_f32_e32 v88, 0xda24260, v81
	v_max_f32_e32 v81, v165, v165
	v_max_f32_e32 v89, 0xda24260, v81
	v_pk_add_f32 v[92:93], v[168:169], 0 neg_lo:[1,1] neg_hi:[1,1]
	v_pk_mul_f32 v[88:89], v[88:89], s[30:31] op_sel_hi:[1,0]
	s_nop 0
	v_div_scale_f32 v81, s[56:57], v88, v88, v92
	v_rcp_f32_e32 v164, v81
	s_nop 0
	v_fma_f32 v165, -v81, v164, 1.0
	v_fmac_f32_e32 v164, v165, v164
	v_div_scale_f32 v165, vcc, v92, v88, v92
	v_mul_f32_e32 v168, v165, v164
	v_fma_f32 v169, -v81, v168, v165
	v_fmac_f32_e32 v168, v169, v164
	v_fma_f32 v81, -v81, v168, v165
	v_div_fmas_f32 v81, v81, v164, v168
	v_div_fixup_f32 v81, v81, v88, v92
	v_div_scale_f32 v88, s[56:57], v89, v89, v93
	v_rcp_f32_e32 v92, v88
	v_cvt_f32_i32_e32 v169, v1
	v_fma_f32 v164, -v88, v92, 1.0
	v_fmac_f32_e32 v92, v164, v92
	v_div_scale_f32 v164, vcc, v93, v89, v93
	v_mul_f32_e32 v165, v164, v92
	v_fma_f32 v168, -v88, v165, v164
	v_fmac_f32_e32 v165, v168, v92
	v_cvt_f32_i32_e32 v168, v0
	v_fma_f32 v88, -v88, v165, v164
	v_div_fmas_f32 v88, v88, v92, v165
	v_div_fixup_f32 v226, v88, v89, v93
	v_pk_mul_f32 v[210:211], v[134:135], v[168:169]
	v_cvt_f32_i32_e32 v169, v29
	v_cvt_f32_i32_e32 v168, v28
	v_cvt_f32_i32_e32 v89, v13
	v_cvt_f32_i32_e32 v88, v12
	v_cvt_f32_i32_e32 v93, v9
	v_pk_mul_f32 v[212:213], v[186:187], v[168:169]
	v_cvt_f32_i32_e32 v169, v25
	v_cvt_f32_i32_e32 v168, v24
	v_cvt_f32_i32_e32 v92, v8
	v_pk_mul_f32 v[88:89], v[190:191], v[88:89]
	v_cvt_f32_i32_e32 v165, v5
	v_pk_mul_f32 v[214:215], v[128:129], v[168:169]
	v_cvt_f32_i32_e32 v169, v21
	v_cvt_f32_i32_e32 v168, v20
	v_pk_mul_f32 v[92:93], v[132:133], v[92:93]
	s_waitcnt lgkmcnt(1)
	v_pk_fma_f32 v[224:225], v[156:157], v[88:89], v[160:161]
	v_cvt_f32_i32_e32 v164, v4
	v_pk_mul_f32 v[216:217], v[184:185], v[168:169]
	v_cvt_f32_i32_e32 v169, v17
	v_cvt_f32_i32_e32 v168, v16
	v_cndmask_b32_e64 v223, v93, v226, s[8:9]
	v_cndmask_b32_e64 v222, v92, v81, s[8:9]
	v_mov_b32_e32 v220, v88
	v_pk_mul_f32 v[218:219], v[130:131], v[168:169]
	v_mov_b32_e32 v221, v89
	v_mov_b32_e32 v168, v218
	v_mov_b32_e32 v169, v219
	v_cndmask_b32_e64 v89, v89, v226, s[10:11]
	v_mov_b32_dpp v168, v168 row_shr:1 row_mask:0xf bank_mask:0xf
	v_mov_b32_dpp v169, v169 row_shr:1 row_mask:0xf bank_mask:0xf
	s_waitcnt lgkmcnt(0)
	v_pk_fma_f32 v[168:169], v[172:173], v[168:169], v[224:225]
	v_cndmask_b32_e64 v88, v88, v81, s[10:11]
	v_pk_fma_f32 v[168:169], v[152:153], v[222:223], v[168:169]
	v_pk_mul_f32 v[164:165], v[188:189], v[164:165]
	v_pk_mul_f32 v[168:169], v[168:169], v[192:193]
	v_mov_b32_dpp v220, v220 row_shl:1 row_mask:0xf bank_mask:0xf
	v_cvt_pk_fp8_f32 v193, v168, v169
	s_nop 0
	v_pk_fma_f32 v[168:169], v[156:157], v[92:93], v[160:161]
	v_mov_b32_dpp v221, v221 row_shl:1 row_mask:0xf bank_mask:0xf
	v_pk_fma_f32 v[88:89], v[172:173], v[88:89], v[168:169]
	s_nop 0
	v_pk_fma_f32 v[88:89], v[152:153], v[164:165], v[88:89]
	s_nop 0
	v_pk_mul_f32 v[88:89], v[88:89], v[148:149]
	v_pk_fma_f32 v[148:149], v[156:157], v[164:165], v[160:161]
	v_cvt_pk_fp8_f32 v192, v88, v89
	s_nop 0
	v_cndmask_b32_e64 v89, v211, v226, s[12:13]
	v_cndmask_b32_e64 v88, v210, v81, s[12:13]
	v_pk_fma_f32 v[92:93], v[172:173], v[92:93], v[148:149]
	s_nop 0
	v_pk_fma_f32 v[88:89], v[152:153], v[88:89], v[92:93]
	v_pk_fma_f32 v[92:93], v[156:157], v[210:211], v[160:161]
	v_pk_mul_f32 v[88:89], v[88:89], v[144:145]
	v_cvt_f32_i32_e32 v145, v63
	v_cvt_pk_fp8_f32 v169, v88, v89
	s_nop 0
	v_cndmask_b32_e64 v89, v165, v226, s[14:15]
	v_cndmask_b32_e64 v88, v164, v81, s[14:15]
	v_pk_fma_f32 v[88:89], v[172:173], v[88:89], v[92:93]
	v_pk_fma_f32 v[92:93], v[156:157], v[212:213], v[160:161]
	v_pk_fma_f32 v[88:89], v[152:153], v[212:213], v[88:89]
	v_pk_fma_f32 v[92:93], v[172:173], v[210:211], v[92:93]
	v_pk_mul_f32 v[88:89], v[88:89], v[140:141]
	s_nop 0
	v_cvt_pk_fp8_f32 v168, v88, v89
	s_nop 0
	v_cndmask_b32_e64 v89, v215, v226, s[22:23]
	v_cndmask_b32_e64 v88, v214, v81, s[22:23]
	v_pk_fma_f32 v[88:89], v[152:153], v[88:89], v[92:93]
	v_pk_fma_f32 v[92:93], v[156:157], v[214:215], v[160:161]
	v_pk_mul_f32 v[88:89], v[88:89], v[200:201]
	s_nop 0
	v_cvt_pk_fp8_f32 v165, v88, v89
	s_nop 0
	v_cndmask_b32_e64 v89, v213, v226, s[20:21]
	v_cndmask_b32_e64 v88, v212, v81, s[20:21]
	v_pk_fma_f32 v[88:89], v[172:173], v[88:89], v[92:93]
	v_pk_fma_f32 v[92:93], v[156:157], v[216:217], v[160:161]
	v_pk_fma_f32 v[88:89], v[152:153], v[216:217], v[88:89]
	v_pk_fma_f32 v[92:93], v[172:173], v[214:215], v[92:93]
	v_pk_mul_f32 v[88:89], v[88:89], v[198:199]
	s_nop 0
	v_cvt_pk_fp8_f32 v164, v88, v89
	s_nop 0
	v_cndmask_b32_e64 v89, v219, v226, s[18:19]
	v_cndmask_b32_e64 v88, v218, v81, s[18:19]
	v_pk_fma_f32 v[88:89], v[152:153], v[88:89], v[92:93]
	v_pk_fma_f32 v[92:93], v[156:157], v[218:219], v[160:161]
	v_pk_mul_f32 v[88:89], v[88:89], v[196:197]
	v_cvt_f32_i32_e32 v161, v51
	v_cvt_pk_fp8_f32 v149, v88, v89
	s_nop 0
	v_cndmask_b32_e64 v89, v217, v226, s[16:17]
	v_cndmask_b32_e64 v88, v216, v81, s[16:17]
	v_pk_fma_f32 v[88:89], v[172:173], v[88:89], v[92:93]
	v_ashrrev_i32_e32 v81, 31, v80
	v_pk_fma_f32 v[88:89], v[152:153], v[220:221], v[88:89]
	v_cvt_f32_i32_e32 v160, v50
	v_pk_mul_f32 v[88:89], v[88:89], v[194:195]
	v_cvt_f32_i32_e32 v153, v59
	v_cvt_pk_fp8_f32 v148, v88, v89
	s_nop 0
	v_lshlrev_b64 v[88:89], 2, v[80:81]
	s_waitcnt vmcnt(0)
	v_mov_b32_e32 v80, v176
	v_mov_b32_e32 v81, v237
	v_mov_b32_e32 v88, v241
	v_mov_b32_e32 v89, v227
	v_pk_mul_f32 v[160:161], v[130:131], v[160:161]
	v_cvt_f32_i32_e32 v152, v58
	v_mov_b32_e32 v172, v160
	v_mov_b32_e32 v173, v161
	v_cvt_f32_i32_e32 v157, v55
	v_mov_b32_dpp v172, v172 row_shr:1 row_mask:0xf bank_mask:0xf
	v_mov_b32_dpp v173, v173 row_shr:1 row_mask:0xf bank_mask:0xf
	v_cvt_f32_i32_e32 v156, v54
	v_pk_mul_f32 v[152:153], v[128:129], v[152:153]
	v_pk_mul_f32 v[156:157], v[184:185], v[156:157]
	s_waitcnt vmcnt(1)
	v_max_f32_e32 v80, v80, v80
	v_max_f32_e32 v81, v81, v81
	v_max_f32_e32 v80, 0xda24260, v80
	v_max_f32_e32 v81, 0xda24260, v81
	s_waitcnt vmcnt(0)
	v_pk_add_f32 v[88:89], v[88:89], 0 neg_lo:[1,1] neg_hi:[1,1]
	v_pk_mul_f32 v[80:81], v[80:81], s[30:31] op_sel_hi:[1,0]
	s_nop 0
	v_div_scale_f32 v92, s[56:57], v80, v80, v88
	v_rcp_f32_e32 v93, v92
	s_nop 0
	v_fma_f32 v140, -v92, v93, 1.0
	v_fmac_f32_e32 v93, v140, v93
	v_div_scale_f32 v140, vcc, v88, v80, v88
	v_mul_f32_e32 v141, v140, v93
	v_fma_f32 v144, -v92, v141, v140
	v_fmac_f32_e32 v141, v144, v93
	v_fma_f32 v92, -v92, v141, v140
	v_div_fmas_f32 v92, v92, v93, v141
	v_div_fixup_f32 v200, v92, v80, v88
	v_div_scale_f32 v80, s[56:57], v81, v81, v89
	v_rcp_f32_e32 v88, v80
	v_cvt_f32_i32_e32 v141, v35
	v_cvt_f32_i32_e32 v144, v62
	v_fma_f32 v92, -v80, v88, 1.0
	v_fmac_f32_e32 v88, v92, v88
	v_div_scale_f32 v92, vcc, v89, v81, v89
	v_mul_f32_e32 v93, v92, v88
	v_fma_f32 v140, -v80, v93, v92
	v_fmac_f32_e32 v93, v140, v88
	v_fma_f32 v80, -v80, v93, v92
	v_div_fmas_f32 v80, v80, v88, v93
	v_div_fixup_f32 v201, v80, v81, v89
	v_cvt_f32_i32_e32 v81, v47
	v_cvt_f32_i32_e32 v80, v46
	v_cvt_f32_i32_e32 v89, v43
	v_cvt_f32_i32_e32 v88, v42
	v_cvt_f32_i32_e32 v93, v39
	v_cvt_f32_i32_e32 v92, v38
	v_pk_mul_f32 v[80:81], v[190:191], v[80:81]
	v_cvt_f32_i32_e32 v140, v34
	v_pk_mul_f32 v[88:89], v[132:133], v[88:89]
	v_pk_fma_f32 v[198:199], v[146:147], v[80:81], v[150:151]
	v_cndmask_b32_e64 v197, v89, v201, s[8:9]
	v_cndmask_b32_e64 v196, v88, v200, s[8:9]
	v_pk_fma_f32 v[172:173], v[138:139], v[172:173], v[198:199]
	v_pk_mul_f32 v[92:93], v[188:189], v[92:93]
	v_mov_b32_e32 v194, v80
	v_mov_b32_e32 v195, v81
	v_pk_fma_f32 v[172:173], v[142:143], v[196:197], v[172:173]
	v_cndmask_b32_e64 v81, v81, v201, s[10:11]
	v_cndmask_b32_e64 v80, v80, v200, s[10:11]
	v_pk_fma_f32 v[196:197], v[146:147], v[88:89], v[150:151]
	v_pk_mul_f32 v[140:141], v[134:135], v[140:141]
	v_pk_fma_f32 v[80:81], v[138:139], v[80:81], v[196:197]
	v_pk_fma_f32 v[198:199], v[146:147], v[92:93], v[150:151]
	v_pk_fma_f32 v[196:197], v[142:143], v[92:93], v[80:81]
	v_cndmask_b32_e64 v81, v141, v201, s[12:13]
	v_cndmask_b32_e64 v80, v140, v200, s[12:13]
	v_pk_fma_f32 v[88:89], v[138:139], v[88:89], v[198:199]
	v_pk_mul_f32 v[144:145], v[186:187], v[144:145]
	v_pk_fma_f32 v[88:89], v[142:143], v[80:81], v[88:89]
	v_cndmask_b32_e64 v81, v93, v201, s[14:15]
	v_cndmask_b32_e64 v80, v92, v200, s[14:15]
	v_pk_fma_f32 v[92:93], v[146:147], v[140:141], v[150:151]
	v_mov_b32_dpp v194, v194 row_shl:1 row_mask:0xf bank_mask:0xf
	v_pk_fma_f32 v[80:81], v[138:139], v[80:81], v[92:93]
	v_pk_fma_f32 v[92:93], v[146:147], v[144:145], v[150:151]
	v_pk_fma_f32 v[198:199], v[142:143], v[144:145], v[80:81]
	v_cndmask_b32_e64 v81, v153, v201, s[22:23]
	v_cndmask_b32_e64 v80, v152, v200, s[22:23]
	v_pk_fma_f32 v[92:93], v[138:139], v[140:141], v[92:93]
	v_mov_b32_dpp v195, v195 row_shl:1 row_mask:0xf bank_mask:0xf
	v_pk_fma_f32 v[140:141], v[142:143], v[80:81], v[92:93]
	v_cndmask_b32_e64 v81, v145, v201, s[20:21]
	v_cndmask_b32_e64 v80, v144, v200, s[20:21]
	v_pk_fma_f32 v[92:93], v[146:147], v[152:153], v[150:151]
	s_nop 0
	v_pk_fma_f32 v[80:81], v[138:139], v[80:81], v[92:93]
	v_pk_fma_f32 v[92:93], v[146:147], v[156:157], v[150:151]
	v_pk_fma_f32 v[144:145], v[142:143], v[156:157], v[80:81]
	v_cndmask_b32_e64 v81, v161, v201, s[18:19]
	v_cndmask_b32_e64 v80, v160, v200, s[18:19]
	v_pk_fma_f32 v[92:93], v[138:139], v[152:153], v[92:93]
	s_nop 0
	v_pk_fma_f32 v[152:153], v[142:143], v[80:81], v[92:93]
	v_cndmask_b32_e64 v81, v157, v201, s[16:17]
	v_cndmask_b32_e64 v80, v156, v200, s[16:17]
	v_pk_fma_f32 v[92:93], v[146:147], v[160:161], v[150:151]
	v_and_b32_e32 v157, 0x7fffffff, v153
	v_pk_fma_f32 v[80:81], v[138:139], v[80:81], v[92:93]
	v_and_b32_e32 v139, 0x7fffffff, v199
	v_pk_fma_f32 v[146:147], v[142:143], v[194:195], v[80:81]
	v_and_b32_e32 v81, 0x7fffffff, v173
	v_and_b32_e32 v80, 0x7fffffff, v172
	v_pk_fma_f32 v[92:93], v[80:81], s[80:81], v[136:137] op_sel_hi:[1,0,0]
	v_and_b32_e32 v195, 0x7fffffff, v197
	v_pk_fma_f32 v[92:93], v[80:81], v[92:93], s[84:85] op_sel_hi:[1,1,0]
	v_and_b32_e32 v194, 0x7fffffff, v196
	v_pk_fma_f32 v[92:93], v[80:81], v[92:93], s[86:87] op_sel_hi:[1,1,0]
	v_pk_fma_f32 v[200:201], v[194:195], s[80:81], v[136:137] op_sel_hi:[1,0,0]
	v_pk_fma_f32 v[92:93], v[80:81], v[92:93], s[82:83] op_sel_hi:[1,1,0]
	v_pk_fma_f32 v[200:201], v[194:195], v[200:201], s[84:85] op_sel_hi:[1,1,0]
	v_pk_fma_f32 v[92:93], v[80:81], v[92:93], s[94:95] op_sel_hi:[1,1,0]
	v_pk_fma_f32 v[200:201], v[194:195], v[200:201], s[86:87] op_sel_hi:[1,1,0]
	v_pk_fma_f32 v[92:93], v[80:81], v[92:93], s[92:93] op_sel_hi:[1,1,0]
	v_and_b32_e32 v143, 0x7fffffff, v89
	v_pk_mul_f32 v[92:93], v[92:93], v[92:93]
	v_and_b32_e32 v142, 0x7fffffff, v88
	v_pk_fma_f32 v[200:201], v[194:195], v[200:201], s[82:83] op_sel_hi:[1,1,0]
	v_pk_mul_f32 v[92:93], v[92:93], v[92:93]
	v_pk_fma_f32 v[210:211], v[142:143], s[80:81], v[136:137] op_sel_hi:[1,0,0]
	v_pk_fma_f32 v[200:201], v[194:195], v[200:201], s[94:95] op_sel_hi:[1,1,0]
	v_pk_mul_f32 v[92:93], v[92:93], v[92:93]
	v_pk_fma_f32 v[210:211], v[142:143], v[210:211], s[84:85] op_sel_hi:[1,1,0]
	v_pk_fma_f32 v[200:201], v[194:195], v[200:201], s[92:93] op_sel_hi:[1,1,0]
	v_pk_mul_f32 v[92:93], v[92:93], v[92:93]
	v_pk_fma_f32 v[210:211], v[142:143], v[210:211], s[86:87] op_sel_hi:[1,1,0]
	v_pk_mul_f32 v[200:201], v[200:201], v[200:201]
	v_rcp_f32_e32 v92, v92
	v_rcp_f32_e32 v93, v93
	v_and_b32_e32 v138, 0x7fffffff, v198
	v_pk_fma_f32 v[210:211], v[142:143], v[210:211], s[82:83] op_sel_hi:[1,1,0]
	v_pk_mul_f32 v[200:201], v[200:201], v[200:201]
	v_pk_fma_f32 v[212:213], v[138:139], s[80:81], v[136:137] op_sel_hi:[1,0,0]
	v_pk_fma_f32 v[210:211], v[142:143], v[210:211], s[94:95] op_sel_hi:[1,1,0]
	v_pk_mul_f32 v[200:201], v[200:201], v[200:201]
	v_pk_fma_f32 v[212:213], v[138:139], v[212:213], s[84:85] op_sel_hi:[1,1,0]
	v_pk_fma_f32 v[210:211], v[142:143], v[210:211], s[92:93] op_sel_hi:[1,1,0]
	v_pk_mul_f32 v[200:201], v[200:201], v[200:201]
	v_max_f32_e32 v173, 0, v173
	v_max_f32_e32 v172, 0, v172
	v_pk_fma_f32 v[212:213], v[138:139], v[212:213], s[86:87] op_sel_hi:[1,1,0]
	v_pk_mul_f32 v[210:211], v[210:211], v[210:211]
	v_pk_fma_f32 v[80:81], v[80:81], v[92:93], v[172:173] neg_lo:[1,0,0] neg_hi:[1,0,0]
	v_rcp_f32_e32 v92, v200
	v_rcp_f32_e32 v93, v201
	v_pk_fma_f32 v[212:213], v[138:139], v[212:213], s[82:83] op_sel_hi:[1,1,0]
	v_pk_mul_f32 v[210:211], v[210:211], v[210:211]
	v_pk_fma_f32 v[212:213], v[138:139], v[212:213], s[94:95] op_sel_hi:[1,1,0]
	v_pk_mul_f32 v[210:211], v[210:211], v[210:211]
	v_pk_fma_f32 v[212:213], v[138:139], v[212:213], s[92:93] op_sel_hi:[1,1,0]
	v_pk_mul_f32 v[210:211], v[210:211], v[210:211]
	v_max_f32_e32 v173, 0, v197
	v_max_f32_e32 v172, 0, v196
	v_pk_mul_f32 v[212:213], v[212:213], v[212:213]
	v_pk_fma_f32 v[92:93], v[194:195], v[92:93], v[172:173] neg_lo:[1,0,0] neg_hi:[1,0,0]
	v_rcp_f32_e32 v172, v210
	v_rcp_f32_e32 v173, v211
	v_pk_mul_f32 v[212:213], v[212:213], v[212:213]
	v_max_f32_e32 v89, 0, v89
	v_pk_mul_f32 v[212:213], v[212:213], v[212:213]
	v_max_f32_e32 v88, 0, v88
	v_pk_mul_f32 v[212:213], v[212:213], v[212:213]
	v_pk_fma_f32 v[88:89], v[142:143], v[172:173], v[88:89] neg_lo:[1,0,0] neg_hi:[1,0,0]
	v_rcp_f32_e32 v142, v212
	v_rcp_f32_e32 v143, v213
	v_max_f32_e32 v173, 0, v199
	v_max_f32_e32 v172, 0, v198
	v_and_b32_e32 v151, 0x7fffffff, v147
	v_pk_fma_f32 v[138:139], v[138:139], v[142:143], v[172:173] neg_lo:[1,0,0] neg_hi:[1,0,0]
	v_and_b32_e32 v143, 0x7fffffff, v141
	v_and_b32_e32 v142, 0x7fffffff, v140
	v_and_b32_e32 v150, 0x7fffffff, v146
	v_and_b32_e32 v156, 0x7fffffff, v152
	v_and_b32_e32 v161, 0x7fffffff, v145
	v_and_b32_e32 v160, 0x7fffffff, v144
	v_pk_fma_f32 v[172:173], v[142:143], s[80:81], v[136:137] op_sel_hi:[1,0,0]
	v_pk_fma_f32 v[194:195], v[160:161], s[80:81], v[136:137] op_sel_hi:[1,0,0]
	v_pk_fma_f32 v[196:197], v[156:157], s[80:81], v[136:137] op_sel_hi:[1,0,0]
	v_pk_fma_f32 v[136:137], v[150:151], s[80:81], v[136:137] op_sel_hi:[1,0,0]
	v_pk_fma_f32 v[172:173], v[142:143], v[172:173], s[84:85] op_sel_hi:[1,1,0]
	v_pk_fma_f32 v[136:137], v[150:151], v[136:137], s[84:85] op_sel_hi:[1,1,0]
	v_pk_fma_f32 v[172:173], v[142:143], v[172:173], s[86:87] op_sel_hi:[1,1,0]
	v_pk_fma_f32 v[136:137], v[150:151], v[136:137], s[86:87] op_sel_hi:[1,1,0]
	v_pk_fma_f32 v[172:173], v[142:143], v[172:173], s[82:83] op_sel_hi:[1,1,0]
	v_pk_fma_f32 v[136:137], v[150:151], v[136:137], s[82:83] op_sel_hi:[1,1,0]
	v_pk_fma_f32 v[172:173], v[142:143], v[172:173], s[94:95] op_sel_hi:[1,1,0]
	v_pk_fma_f32 v[194:195], v[160:161], v[194:195], s[84:85] op_sel_hi:[1,1,0]
	v_pk_fma_f32 v[136:137], v[150:151], v[136:137], s[94:95] op_sel_hi:[1,1,0]
	v_pk_fma_f32 v[172:173], v[142:143], v[172:173], s[92:93] op_sel_hi:[1,1,0]
	v_pk_fma_f32 v[194:195], v[160:161], v[194:195], s[86:87] op_sel_hi:[1,1,0]
	v_pk_fma_f32 v[136:137], v[150:151], v[136:137], s[92:93] op_sel_hi:[1,1,0]
	v_pk_mul_f32 v[172:173], v[172:173], v[172:173]
	v_pk_fma_f32 v[194:195], v[160:161], v[194:195], s[82:83] op_sel_hi:[1,1,0]
	v_pk_mul_f32 v[136:137], v[136:137], v[136:137]
	v_pk_mul_f32 v[172:173], v[172:173], v[172:173]
	v_pk_fma_f32 v[194:195], v[160:161], v[194:195], s[94:95] op_sel_hi:[1,1,0]
	v_pk_mul_f32 v[136:137], v[136:137], v[136:137]
	v_pk_mul_f32 v[172:173], v[172:173], v[172:173]
	v_pk_fma_f32 v[196:197], v[156:157], v[196:197], s[84:85] op_sel_hi:[1,1,0]
	v_pk_fma_f32 v[194:195], v[160:161], v[194:195], s[92:93] op_sel_hi:[1,1,0]
	v_pk_mul_f32 v[136:137], v[136:137], v[136:137]
	v_pk_mul_f32 v[172:173], v[172:173], v[172:173]
	v_pk_fma_f32 v[196:197], v[156:157], v[196:197], s[86:87] op_sel_hi:[1,1,0]
	v_pk_mul_f32 v[194:195], v[194:195], v[194:195]
	v_pk_mul_f32 v[198:199], v[136:137], v[136:137]
	v_rcp_f32_e32 v136, v172
	v_rcp_f32_e32 v137, v173
	v_pk_fma_f32 v[196:197], v[156:157], v[196:197], s[82:83] op_sel_hi:[1,1,0]
	v_pk_mul_f32 v[194:195], v[194:195], v[194:195]
	v_pk_fma_f32 v[196:197], v[156:157], v[196:197], s[94:95] op_sel_hi:[1,1,0]
	v_pk_mul_f32 v[194:195], v[194:195], v[194:195]
	v_pk_fma_f32 v[196:197], v[156:157], v[196:197], s[92:93] op_sel_hi:[1,1,0]
	v_pk_mul_f32 v[194:195], v[194:195], v[194:195]
	v_max_f32_e32 v141, 0, v141
	v_max_f32_e32 v140, 0, v140
	v_pk_mul_f32 v[196:197], v[196:197], v[196:197]
	v_pk_fma_f32 v[142:143], v[142:143], v[136:137], v[140:141] neg_lo:[1,0,0] neg_hi:[1,0,0]
	v_rcp_f32_e32 v136, v194
	v_rcp_f32_e32 v137, v195
	v_pk_mul_f32 v[196:197], v[196:197], v[196:197]
	v_max_f32_e32 v141, 0, v145
	v_pk_mul_f32 v[196:197], v[196:197], v[196:197]
	v_max_f32_e32 v140, 0, v144
	v_pk_mul_f32 v[196:197], v[196:197], v[196:197]
	v_pk_fma_f32 v[136:137], v[160:161], v[136:137], v[140:141] neg_lo:[1,0,0] neg_hi:[1,0,0]
	v_rcp_f32_e32 v140, v196
	v_rcp_f32_e32 v141, v197
	v_max_f32_e32 v145, 0, v153
	v_max_f32_e32 v144, 0, v152
	v_max_f32_e32 v147, 0, v147
	v_pk_fma_f32 v[144:145], v[156:157], v[140:141], v[144:145] neg_lo:[1,0,0] neg_hi:[1,0,0]
	v_rcp_f32_e32 v140, v198
	v_rcp_f32_e32 v141, v199
	v_max_f32_e32 v146, 0, v146
	v_cvt_f32_i32_e32 v161, v19
	v_pk_fma_f32 v[140:141], v[150:151], v[140:141], v[146:147] neg_lo:[1,0,0] neg_hi:[1,0,0]
	v_max_f32_e32 v146, v166, v166
	v_max_f32_e32 v147, v167, v167
	v_max_f32_e32 v146, 0xda24260, v146
	v_max_f32_e32 v147, 0xda24260, v147
	v_pk_add_f32 v[150:151], v[170:171], 0 neg_lo:[1,1] neg_hi:[1,1]
	v_pk_mul_f32 v[146:147], v[146:147], s[30:31] op_sel_hi:[1,0]
	s_nop 0
	v_div_scale_f32 v152, s[56:57], v146, v146, v150
	v_rcp_f32_e32 v153, v152
	s_nop 0
	v_fma_f32 v156, -v152, v153, 1.0
	v_fmac_f32_e32 v153, v156, v153
	v_div_scale_f32 v156, vcc, v150, v146, v150
	v_mul_f32_e32 v157, v156, v153
	v_fma_f32 v160, -v152, v157, v156
	v_fmac_f32_e32 v157, v160, v153
	v_fma_f32 v152, -v152, v157, v156
	v_div_fmas_f32 v152, v152, v153, v157
	v_div_fixup_f32 v194, v152, v146, v150
	v_div_scale_f32 v146, s[56:57], v147, v147, v151
	v_rcp_f32_e32 v150, v146
	v_cvt_f32_i32_e32 v160, v18
	v_cvt_f32_i32_e32 v157, v27
	v_fma_f32 v152, -v146, v150, 1.0
	v_fmac_f32_e32 v150, v152, v150
	v_div_scale_f32 v152, vcc, v151, v147, v151
	v_mul_f32_e32 v153, v152, v150
	v_fma_f32 v156, -v146, v153, v152
	v_fmac_f32_e32 v153, v156, v150
	v_fma_f32 v146, -v146, v153, v152
	v_div_fmas_f32 v146, v146, v150, v153
	v_div_fixup_f32 v195, v146, v147, v151
	v_cvt_f32_i32_e32 v147, v15
	v_cvt_f32_i32_e32 v146, v14
	v_cvt_f32_i32_e32 v151, v11
	v_cvt_f32_i32_e32 v150, v10
	v_pk_mul_f32 v[130:131], v[130:131], v[160:161]
	v_pk_mul_f32 v[146:147], v[190:191], v[146:147]
	v_mov_b32_e32 v160, v130
	v_mov_b32_e32 v161, v131
	v_pk_mul_f32 v[132:133], v[132:133], v[150:151]
	v_mov_b32_dpp v160, v160 row_shr:1 row_mask:0xf bank_mask:0xf
	v_mov_b32_dpp v161, v161 row_shr:1 row_mask:0xf bank_mask:0xf
	v_pk_fma_f32 v[172:173], v[158:159], v[146:147], v[162:163]
	v_cvt_f32_i32_e32 v151, v7
	v_cvt_f32_i32_e32 v150, v6
	v_cndmask_b32_e64 v171, v133, v195, s[8:9]
	v_cndmask_b32_e64 v170, v132, v194, s[8:9]
	v_pk_fma_f32 v[160:161], v[174:175], v[160:161], v[172:173]
	v_cvt_f32_i32_e32 v153, v3
	v_pk_fma_f32 v[160:161], v[154:155], v[170:171], v[160:161]
	v_cvt_f32_i32_e32 v152, v2
	v_pk_mul_f32 v[80:81], v[160:161], v[80:81]
	v_mov_b32_e32 v166, v146
	v_mov_b32_e32 v167, v147
	v_cvt_pk_fp8_f32 v193, v80, v81 op_sel:[0,0,1]
	s_nop 0
	v_cndmask_b32_e64 v81, v147, v195, s[10:11]
	v_cndmask_b32_e64 v80, v146, v194, s[10:11]
	v_pk_fma_f32 v[146:147], v[158:159], v[132:133], v[162:163]
	v_pk_mul_f32 v[150:151], v[188:189], v[150:151]
	v_pk_fma_f32 v[80:81], v[174:175], v[80:81], v[146:147]
	v_pk_mul_f32 v[134:135], v[134:135], v[152:153]
	v_pk_fma_f32 v[80:81], v[154:155], v[150:151], v[80:81]
	v_cvt_f32_i32_e32 v153, v31
	v_pk_mul_f32 v[80:81], v[80:81], v[92:93]
	v_pk_fma_f32 v[92:93], v[158:159], v[150:151], v[162:163]
	v_cvt_f32_i32_e32 v152, v30
	v_cvt_pk_fp8_f32 v192, v80, v81 op_sel:[0,0,1]
	s_nop 0
	v_cndmask_b32_e64 v81, v135, v195, s[12:13]
	v_cndmask_b32_e64 v80, v134, v194, s[12:13]
	v_pk_fma_f32 v[92:93], v[174:175], v[132:133], v[92:93]
	v_cvt_f32_i32_e32 v156, v26
	v_pk_fma_f32 v[80:81], v[154:155], v[80:81], v[92:93]
	v_pk_mul_f32 v[152:153], v[186:187], v[152:153]
	v_pk_mul_f32 v[80:81], v[80:81], v[88:89]
	v_pk_fma_f32 v[88:89], v[158:159], v[134:135], v[162:163]
	v_cvt_pk_fp8_f32 v169, v80, v81 op_sel:[0,0,1]
	s_nop 0
	v_cndmask_b32_e64 v81, v151, v195, s[14:15]
	v_cndmask_b32_e64 v80, v150, v194, s[14:15]
	v_pk_fma_f32 v[80:81], v[174:175], v[80:81], v[88:89]
	v_pk_mul_f32 v[128:129], v[128:129], v[156:157]
	v_pk_fma_f32 v[80:81], v[154:155], v[152:153], v[80:81]
	v_pk_fma_f32 v[88:89], v[158:159], v[152:153], v[162:163]
	v_pk_mul_f32 v[80:81], v[80:81], v[138:139]
	v_cvt_f32_i32_e32 v157, v23
	v_cvt_f32_i32_e32 v156, v22
	v_cvt_pk_fp8_f32 v168, v80, v81 op_sel:[0,0,1]
	s_nop 0
	v_cndmask_b32_e64 v81, v129, v195, s[22:23]
	v_cndmask_b32_e64 v80, v128, v194, s[22:23]
	v_pk_fma_f32 v[88:89], v[174:175], v[134:135], v[88:89]
	v_pk_mul_f32 v[156:157], v[184:185], v[156:157]
	v_pk_fma_f32 v[80:81], v[154:155], v[80:81], v[88:89]
	v_pk_fma_f32 v[88:89], v[158:159], v[128:129], v[162:163]
	v_pk_mul_f32 v[80:81], v[80:81], v[142:143]
	v_mov_b32_dpp v166, v166 row_shl:1 row_mask:0xf bank_mask:0xf
	v_cvt_pk_fp8_f32 v165, v80, v81 op_sel:[0,0,1]
	s_nop 0
	v_cndmask_b32_e64 v81, v153, v195, s[20:21]
	v_cndmask_b32_e64 v80, v152, v194, s[20:21]
	v_pk_fma_f32 v[80:81], v[174:175], v[80:81], v[88:89]
	v_pk_fma_f32 v[88:89], v[158:159], v[156:157], v[162:163]
	v_pk_fma_f32 v[80:81], v[154:155], v[156:157], v[80:81]
	v_pk_fma_f32 v[88:89], v[174:175], v[128:129], v[88:89]
	v_pk_mul_f32 v[80:81], v[80:81], v[136:137]
	v_mov_b32_dpp v167, v167 row_shl:1 row_mask:0xf bank_mask:0xf
	v_cvt_pk_fp8_f32 v164, v80, v81 op_sel:[0,0,1]
	s_nop 0
	v_cndmask_b32_e64 v81, v131, v195, s[18:19]
	v_cndmask_b32_e64 v80, v130, v194, s[18:19]
	v_pk_fma_f32 v[80:81], v[154:155], v[80:81], v[88:89]
	v_pk_fma_f32 v[88:89], v[158:159], v[130:131], v[162:163]
	v_pk_mul_f32 v[80:81], v[80:81], v[144:145]
	s_nop 0
	v_cvt_pk_fp8_f32 v149, v80, v81 op_sel:[0,0,1]
	s_nop 0
	v_cndmask_b32_e64 v81, v157, v195, s[16:17]
	v_cndmask_b32_e64 v80, v156, v194, s[16:17]
	v_pk_fma_f32 v[80:81], v[174:175], v[80:81], v[88:89]
	s_nop 0
	v_pk_fma_f32 v[80:81], v[154:155], v[166:167], v[80:81]
	s_nop 0
	v_pk_mul_f32 v[80:81], v[80:81], v[140:141]
	s_nop 0
	v_cvt_pk_fp8_f32 v148, v80, v81 op_sel:[0,0,1]
	s_nop 0
	s_and_saveexec_b64 s[8:9], s[42:43]
	s_cbranch_execnz .LBB0_716
	s_or_b64 exec, exec, s[8:9]
	s_and_saveexec_b64 s[8:9], s[44:45]
	s_cbranch_execnz .LBB0_717
